# barrier waiters poll TOPGEN directly; removed redundant setprio 0/1 pairs inside MFMA clusters
# speedup vs baseline: 1.0384x; 1.0035x over previous
; __device__ __forceinline__ unsigned xb_ld(unsigned* p)              { return __hip_atomic_load(p, __ATOMIC_RELAXED, __HIP_MEMORY_SCOPE_AGENT); }
; __device__ __forceinline__ unsigned xb_add(unsigned* p, unsigned v) { return __hip_atomic_fetch_add(p, v, __ATOMIC_RELAXED, __HIP_MEMORY_SCOPE_AGENT); }
; #define XB_SPIN(cond, bar) do { unsigned _sp = 0; while (cond) { __builtin_amdgcn_s_sleep(1); \
;     if ((++_sp & 255u) == 0u) { if (xb_ld(&(bar)[XB_TMO])) break; if (_sp > XB_SPIN_CAP) { atomicAdd(&(bar)[XB_TMO], 1u); break; } } } } while (0)
; __device__ __forceinline__ void xcd_barrier(const XcdBarrier& b) {
;     ...
;         const unsigned old = xb_add(&bar[XB_XSUB(b.x)], 1u);
;         const unsigned gen = old / nloc;
;         if (old + 1u == (gen + 1u) * nloc) {
;             __builtin_amdgcn_fence(__ATOMIC_RELEASE, "agent");
;             asm volatile("s_waitcnt vmcnt(0)" ::: "memory");
;             const unsigned og = xb_add(&bar[XB_TOP], 1u);
;             const unsigned tg = og / nx;
;             if (og + 1u == (tg + 1u) * nx) xb_add(&bar[XB_TOPGEN], 1u);
;             else XB_SPIN(xb_ld(&bar[XB_TOPGEN]) == tg, bar);
;             __builtin_amdgcn_fence(__ATOMIC_ACQUIRE, "agent");
;             xb_add(&bar[XB_XGEN(b.x)], 1u);
;             asm volatile("s_waitcnt vmcnt(0)" ::: "memory");
;         } else {
;             XB_SPIN(xb_ld(&bar[XB_XGEN(b.x)]) == gen, bar);
.LBB0_79:
	s_or_b64 exec, exec, s[6:7]
	v_cvt_f32_u32_e32 v4, v2
	s_waitcnt vmcnt(0)
	v_readfirstlane_b32 s4, v3
	v_sub_u32_e32 v3, 0, v2
	v_rcp_iflag_f32_e32 v4, v4
	v_add_u32_e32 v5, s4, v1
	v_mul_f32_e32 v4, 0x4f7ffffe, v4
	v_cvt_u32_f32_e32 v4, v4
	v_mul_lo_u32 v1, v3, v4
	v_mul_hi_u32 v1, v4, v1
	v_add_u32_e32 v1, v4, v1
	v_mul_hi_u32 v1, v5, v1
	v_mul_lo_u32 v3, v1, v2
	v_sub_u32_e32 v3, v5, v3
	v_add_u32_e32 v4, 1, v1
	v_cmp_ge_u32_e32 vcc, v3, v2
	s_nop 1
	v_cndmask_b32_e32 v1, v1, v4, vcc
	v_sub_u32_e32 v4, v3, v2
	v_cndmask_b32_e32 v3, v3, v4, vcc
	v_add_u32_e32 v4, 1, v1
	v_cmp_ge_u32_e32 vcc, v3, v2
	v_add_u32_e32 v3, 1, v5
	s_nop 0
	v_cndmask_b32_e32 v1, v1, v4, vcc
	v_mul_lo_u32 v4, v2, v1
	v_add_u32_e32 v2, v4, v2
	v_cmp_ne_u32_e32 vcc, v3, v2
	s_and_saveexec_b64 s[4:5], vcc
	s_xor_b64 s[4:5], exec, s[4:5]
	s_cbranch_execz .LBB0_93
	s_waitcnt lgkmcnt(0)
	v_readlane_b32 s8, v237, 8
	v_readlane_b32 s9, v237, 9
	v_mov_b32_e32 v0, 0
	s_add_u32 s8, s8, 0x3500
	s_addc_u32 s9, s9, 0
	global_load_dword v0, v0, s[8:9] sc1
	s_waitcnt vmcnt(0)
	v_cmp_eq_u32_e32 vcc, v0, v1
	s_and_saveexec_b64 s[6:7], vcc
	s_cbranch_execz .LBB0_92
	s_mov_b32 s20, 1
	s_mov_b64 s[10:11], 0
	v_mov_b32_e32 v0, 0
	s_branch .LBB0_83

; __device__ __forceinline__ unsigned xb_add(unsigned* p, unsigned v) { return __hip_atomic_fetch_add(p, v, __ATOMIC_RELAXED, __HIP_MEMORY_SCOPE_AGENT); }
; __device__ __forceinline__ void xcd_barrier(const XcdBarrier& b) {
;     ...
;             __builtin_amdgcn_fence(__ATOMIC_ACQUIRE, "agent");
;             xb_add(&bar[XB_XGEN(b.x)], 1u);
;             asm volatile("s_waitcnt vmcnt(0)" ::: "memory");
.LBB0_110:
	s_or_b64 exec, exec, s[4:5]
	s_mov_b64 s[4:5], exec
	v_mbcnt_lo_u32_b32 v0, s4, 0
	v_mbcnt_hi_u32_b32 v0, s5, v0
	v_cmp_eq_u32_e32 vcc, 0, v0
	s_waitcnt vmcnt(0)
	buffer_inv sc1
	s_and_saveexec_b64 s[6:7], vcc
	s_cbranch_execz .LBB0_112
	s_bcnt1_i32_b64 s4, s[4:5]
.LBB0_112:
	s_or_b64 exec, exec, s[6:7]
	s_waitcnt vmcnt(0)

; #define PG8_STAGE(bufoff, gbase, voff) do { _Pragma("unroll") for (int _i = 0; _i < 2; ++_i) \
;         __builtin_amdgcn_global_load_lds((const unsigned*)((const char*)(gbase) + (voff)[_i]), (LAS unsigned*)(lds + (bufoff) + ldsw + _i * 8192), 16, 0, 0); } while (0)
; #define PG8_LDA(dst, b, h) do { _Pragma("unroll") for (int m = 0; m < 4; ++m) _Pragma("unroll") for (int k = 0; k < 2; ++k) dst[m][k] = *(const LAS bf16x8*)(lds + PG8_SA(b, h) + aoff + m * 2048 + k * 1024); } while (0)
; #define PG8_LDB(dst, b, h) do { _Pragma("unroll") for (int n = 0; n < 2; ++n) _Pragma("unroll") for (int k = 0; k < 2; ++k) dst[n][k] = *(const LAS bf16x8*)(lds + PG8_SB(b, h) + boff + n * 2048 + k * 1024); } while (0)
; #define PG8_MMA(ai, bj, At, Bt) do { __builtin_amdgcn_s_setprio(1); _Pragma("unroll") for (int m = 0; m < 4; ++m) _Pragma("unroll") for (int n = 0; n < 2; ++n) _Pragma("unroll") for (int k = 0; k < 2; ++k) \
;         acc[ai][bj][m][n] = __builtin_amdgcn_mfma_f32_16x16x32_bf16(Bt[n][k], At[m][k], acc[ai][bj][m][n], 0, 0, 0); __builtin_amdgcn_s_setprio(0); } while (0)
; #define PG8_WAIT_V(n) asm volatile("s_waitcnt vmcnt(" #n ")" ::: "memory")
; #define PG8_WAIT_L(n) asm volatile("s_waitcnt lgkmcnt(" #n ")" ::: "memory")
; #define PG8_BAR __builtin_amdgcn_s_barrier()
; #define PG8_SCHED __builtin_amdgcn_sched_barrier(0)
; template <class Epi, class Sched, bool ALIGN_EPI = true>
; __device__ __forceinline__ void gemm_phase(LAS unsigned char* lds, const Gemm g, const Sched& S, const Epi& E) {
;     ...
;             const bool last = (t == nt - 2);
;             const char* a1 = cA + (size_t)(t + 1) * kstep;
;             const char* a2 = last ? nA : cA + (size_t)(t + 2) * kstep; const char* b2 = last ? nB : cB + (size_t)(t + 2) * kstep;
;             const char* a3 = a2 + kstep; const char* b3 = b2 + kstep;
;             PG8_LDB(B0, 0, 0); PG8_LDB(B1, 0, 1); PG8_SCHED; PG8_LDA(At, 0, 0); PG8_STAGE(PG8_SA(1, 1), a1 + hsA, voffA);
;             PG8_WAIT_V(8); PG8_WAIT_L(0); PG8_BAR; PG8_MMA(0, 0, At, B0); PG8_MMA(0, 1, At, B1); PG8_BAR; PG8_SCHED;
;             PG8_LDA(At, 0, 1); PG8_STAGE(PG8_SB(0, 0), b2, voffB); PG8_STAGE(PG8_SB(0, 1), b2 + hsB, voffB); PG8_STAGE(PG8_SA(0, 0), a2, voffA);
;             PG8_WAIT_V(8); PG8_WAIT_L(0); PG8_BAR; PG8_MMA(1, 0, At, B0); PG8_MMA(1, 1, At, B1); PG8_BAR; PG8_SCHED;
.LBB0_134:
	ds_read_b128 v[146:149], v158
	ds_read_b128 v[162:165], v158 offset:1024
	ds_read_b128 v[166:169], v158 offset:2048
	ds_read_b128 v[170:173], v158 offset:3072
	ds_read_b128 v[174:177], v159
	ds_read_b128 v[182:185], v159 offset:1024
	ds_read_b128 v[186:189], v159 offset:2048
	ds_read_b128 v[190:193], v159 offset:3072
	s_add_u32 s6, s4, 0xfffc0080
	s_addc_u32 s7, s5, -1
	s_cmp_eq_u32 s58, 12
	s_cselect_b32 s9, s19, s7
	s_cselect_b32 s8, s18, s6
	s_cselect_b32 s7, s3, s33
	s_cselect_b32 s6, s17, s23
	v_lshl_add_u64 v[150:151], s[4:5], 0, v[138:139]
	s_add_i32 m0, s25, 0xc000
	ds_read_b128 v[194:197], v160
	ds_read_b128 v[198:201], v160 offset:1024
	ds_read_b128 v[202:205], v160 offset:2048
	ds_read_b128 v[206:209], v160 offset:3072
	ds_read_b128 v[210:213], v160 offset:4096
	ds_read_b128 v[214:217], v160 offset:5120
	ds_read_b128 v[218:221], v160 offset:6144
	ds_read_b128 v[222:225], v160 offset:7168
	global_load_lds_dwordx4 v[150:151], off
	v_lshl_add_u64 v[150:151], s[4:5], 0, v[140:141]
	s_add_i32 m0, s25, 0xe000
	s_nop 0
	global_load_lds_dwordx4 v[150:151], off
	s_waitcnt vmcnt(8)
	s_waitcnt lgkmcnt(0)
	s_barrier
	s_setprio 1
	s_waitcnt lgkmcnt(0)
	v_mfma_f32_16x16x32_bf16 v[124:127], v[146:149], v[194:197], v[124:127]
	v_mfma_f32_16x16x32_bf16 v[120:123], v[166:169], v[194:197], v[120:123]
	v_mfma_f32_16x16x32_bf16 v[108:111], v[146:149], v[202:205], v[108:111]
	v_mfma_f32_16x16x32_bf16 v[104:107], v[166:169], v[202:205], v[104:107]
	v_mfma_f32_16x16x32_bf16 v[92:95], v[146:149], v[210:213], v[92:95]
	v_mfma_f32_16x16x32_bf16 v[88:91], v[166:169], v[210:213], v[88:91]
	v_mfma_f32_16x16x32_bf16 v[76:79], v[146:149], v[218:221], v[76:79]
	v_mfma_f32_16x16x32_bf16 v[72:75], v[166:169], v[218:221], v[72:75]
	v_mfma_f32_16x16x32_bf16 v[124:127], v[162:165], v[198:201], v[124:127]
	v_mfma_f32_16x16x32_bf16 v[120:123], v[170:173], v[198:201], v[120:123]
	v_mfma_f32_16x16x32_bf16 v[108:111], v[162:165], v[206:209], v[108:111]
	v_mfma_f32_16x16x32_bf16 v[104:107], v[170:173], v[206:209], v[104:107]
	v_mfma_f32_16x16x32_bf16 v[92:95], v[162:165], v[214:217], v[92:95]
	v_mfma_f32_16x16x32_bf16 v[88:91], v[170:173], v[214:217], v[88:91]
	v_mfma_f32_16x16x32_bf16 v[76:79], v[162:165], v[222:225], v[76:79]
	v_mfma_f32_16x16x32_bf16 v[72:75], v[170:173], v[222:225], v[72:75]
	v_mfma_f32_16x16x32_bf16 v[116:119], v[174:177], v[194:197], v[116:119]
	v_mfma_f32_16x16x32_bf16 v[112:115], v[186:189], v[194:197], v[112:115]
	v_mfma_f32_16x16x32_bf16 v[100:103], v[174:177], v[202:205], v[100:103]
	v_mfma_f32_16x16x32_bf16 v[96:99], v[186:189], v[202:205], v[96:99]
	v_mfma_f32_16x16x32_bf16 v[84:87], v[174:177], v[210:213], v[84:87]
	v_mfma_f32_16x16x32_bf16 v[80:83], v[186:189], v[210:213], v[80:83]
	v_mfma_f32_16x16x32_bf16 v[68:71], v[174:177], v[218:221], v[68:71]
	v_mfma_f32_16x16x32_bf16 v[64:67], v[186:189], v[218:221], v[64:67]
	v_mfma_f32_16x16x32_bf16 v[116:119], v[182:185], v[198:201], v[116:119]
	v_mfma_f32_16x16x32_bf16 v[112:115], v[190:193], v[198:201], v[112:115]
	v_mfma_f32_16x16x32_bf16 v[100:103], v[182:185], v[206:209], v[100:103]
	v_mfma_f32_16x16x32_bf16 v[96:99], v[190:193], v[206:209], v[96:99]
	v_mfma_f32_16x16x32_bf16 v[84:87], v[182:185], v[214:217], v[84:87]
	v_mfma_f32_16x16x32_bf16 v[80:83], v[190:193], v[214:217], v[80:83]
	v_mfma_f32_16x16x32_bf16 v[68:71], v[182:185], v[222:225], v[68:71]
	v_mfma_f32_16x16x32_bf16 v[64:67], v[190:193], v[222:225], v[64:67]
	s_setprio 0
	s_barrier
	s_add_i32 s59, s48, s24
	v_lshl_add_u64 v[150:151], s[6:7], 0, v[130:131]
	s_mov_b32 m0, s59
	ds_read_b128 v[194:197], v160 offset:16384
	ds_read_b128 v[198:201], v160 offset:17408
	ds_read_b128 v[202:205], v160 offset:18432
	ds_read_b128 v[206:209], v160 offset:19456
	ds_read_b128 v[210:213], v160 offset:20480
	ds_read_b128 v[214:217], v160 offset:21504
	ds_read_b128 v[218:221], v160 offset:22528
	ds_read_b128 v[222:225], v160 offset:23552
	global_load_lds_dwordx4 v[150:151], off
	s_add_i32 m0, s59, 0x2000
	s_add_u32 s60, s6, 0x40000
	v_lshl_add_u64 v[178:179], s[6:7], 0, v[134:135]
	s_addc_u32 s61, s7, 0
	s_add_i32 s59, s49, s24
	global_load_lds_dwordx4 v[178:179], off
	v_lshl_add_u64 v[226:227], s[60:61], 0, v[130:131]
	s_mov_b32 m0, s59
	v_lshl_add_u64 v[228:229], s[8:9], 0, v[132:133]
	global_load_lds_dwordx4 v[226:227], off
	v_lshl_add_u64 v[226:227], s[60:61], 0, v[134:135]
	s_add_i32 m0, s59, 0x2000
	s_nop 0
	global_load_lds_dwordx4 v[226:227], off
	v_lshl_add_u64 v[226:227], s[8:9], 0, v[128:129]
	s_mov_b32 m0, s25
	s_nop 0
	global_load_lds_dwordx4 v[226:227], off
	s_mov_b32 m0, s26
	s_nop 0
	global_load_lds_dwordx4 v[228:229], off
	s_waitcnt vmcnt(8)
	s_waitcnt lgkmcnt(0)
	s_barrier
; #define PG8_STAGE(bufoff, gbase, voff) do { _Pragma("unroll") for (int _i = 0; _i < 2; ++_i) \
;         __builtin_amdgcn_global_load_lds((const unsigned*)((const char*)(gbase) + (voff)[_i]), (LAS unsigned*)(lds + (bufoff) + ldsw + _i * 8192), 16, 0, 0); } while (0)
; #define PG8_LDA(dst, b, h) do { _Pragma("unroll") for (int m = 0; m < 4; ++m) _Pragma("unroll") for (int k = 0; k < 2; ++k) dst[m][k] = *(const LAS bf16x8*)(lds + PG8_SA(b, h) + aoff + m * 2048 + k * 1024); } while (0)
; #define PG8_LDB(dst, b, h) do { _Pragma("unroll") for (int n = 0; n < 2; ++n) _Pragma("unroll") for (int k = 0; k < 2; ++k) dst[n][k] = *(const LAS bf16x8*)(lds + PG8_SB(b, h) + boff + n * 2048 + k * 1024); } while (0)
; #define PG8_MMA(ai, bj, At, Bt) do { __builtin_amdgcn_s_setprio(1); _Pragma("unroll") for (int m = 0; m < 4; ++m) _Pragma("unroll") for (int n = 0; n < 2; ++n) _Pragma("unroll") for (int k = 0; k < 2; ++k) \
;         acc[ai][bj][m][n] = __builtin_amdgcn_mfma_f32_16x16x32_bf16(Bt[n][k], At[m][k], acc[ai][bj][m][n], 0, 0, 0); __builtin_amdgcn_s_setprio(0); } while (0)
; #define PG8_WAIT_V(n) asm volatile("s_waitcnt vmcnt(" #n ")" ::: "memory")
; #define PG8_WAIT_L(n) asm volatile("s_waitcnt lgkmcnt(" #n ")" ::: "memory")
; #define PG8_BAR __builtin_amdgcn_s_barrier()
; #define PG8_SCHED __builtin_amdgcn_sched_barrier(0)
; template <class Epi, class Sched, bool ALIGN_EPI = true>
; __device__ __forceinline__ void gemm_phase(LAS unsigned char* lds, const Gemm g, const Sched& S, const Epi& E) {
;     ...
;             PG8_WAIT_V(8); PG8_WAIT_L(0); PG8_BAR; PG8_MMA(1, 0, At, B0); PG8_MMA(1, 1, At, B1); PG8_BAR; PG8_SCHED;
;             PG8_LDB(B0, 1, 0); PG8_LDB(B1, 1, 1); PG8_SCHED; PG8_LDA(At, 1, 0); PG8_STAGE(PG8_SA(0, 1), a2 + hsA, voffA);
;             PG8_WAIT_V(8); PG8_WAIT_L(0); PG8_BAR; PG8_MMA(0, 0, At, B0); PG8_MMA(0, 1, At, B1); PG8_BAR; PG8_SCHED;
	s_setprio 1
	s_waitcnt lgkmcnt(0)
	v_mfma_f32_16x16x32_bf16 v[60:63], v[146:149], v[194:197], v[60:63]
	v_mfma_f32_16x16x32_bf16 v[56:59], v[166:169], v[194:197], v[56:59]
	v_mfma_f32_16x16x32_bf16 v[44:47], v[146:149], v[202:205], v[44:47]
	v_mfma_f32_16x16x32_bf16 v[40:43], v[166:169], v[202:205], v[40:43]
	v_mfma_f32_16x16x32_bf16 v[28:31], v[146:149], v[210:213], v[28:31]
	v_mfma_f32_16x16x32_bf16 v[24:27], v[166:169], v[210:213], v[24:27]
	v_mfma_f32_16x16x32_bf16 v[12:15], v[146:149], v[218:221], v[12:15]
	v_mfma_f32_16x16x32_bf16 v[8:11], v[166:169], v[218:221], v[8:11]
	v_mfma_f32_16x16x32_bf16 v[60:63], v[162:165], v[198:201], v[60:63]
	v_mfma_f32_16x16x32_bf16 v[56:59], v[170:173], v[198:201], v[56:59]
	v_mfma_f32_16x16x32_bf16 v[44:47], v[162:165], v[206:209], v[44:47]
	v_mfma_f32_16x16x32_bf16 v[40:43], v[170:173], v[206:209], v[40:43]
	v_mfma_f32_16x16x32_bf16 v[28:31], v[162:165], v[214:217], v[28:31]
	v_mfma_f32_16x16x32_bf16 v[24:27], v[170:173], v[214:217], v[24:27]
	v_mfma_f32_16x16x32_bf16 v[12:15], v[162:165], v[222:225], v[12:15]
	v_mfma_f32_16x16x32_bf16 v[8:11], v[170:173], v[222:225], v[8:11]
	v_mfma_f32_16x16x32_bf16 v[52:55], v[174:177], v[194:197], v[52:55]
	v_mfma_f32_16x16x32_bf16 v[48:51], v[186:189], v[194:197], v[48:51]
	v_mfma_f32_16x16x32_bf16 v[36:39], v[174:177], v[202:205], v[36:39]
	v_mfma_f32_16x16x32_bf16 v[32:35], v[186:189], v[202:205], v[32:35]
	v_mfma_f32_16x16x32_bf16 v[20:23], v[174:177], v[210:213], v[20:23]
	v_mfma_f32_16x16x32_bf16 v[16:19], v[186:189], v[210:213], v[16:19]
	v_mfma_f32_16x16x32_bf16 v[4:7], v[174:177], v[218:221], v[4:7]
	v_mfma_f32_16x16x32_bf16 v[0:3], v[186:189], v[218:221], v[0:3]
	v_mfma_f32_16x16x32_bf16 v[52:55], v[182:185], v[198:201], v[52:55]
	v_mfma_f32_16x16x32_bf16 v[48:51], v[190:193], v[198:201], v[48:51]
	v_mfma_f32_16x16x32_bf16 v[36:39], v[182:185], v[206:209], v[36:39]
	v_mfma_f32_16x16x32_bf16 v[32:35], v[190:193], v[206:209], v[32:35]
	v_mfma_f32_16x16x32_bf16 v[20:23], v[182:185], v[214:217], v[20:23]
	v_mfma_f32_16x16x32_bf16 v[16:19], v[190:193], v[214:217], v[16:19]
	v_mfma_f32_16x16x32_bf16 v[4:7], v[182:185], v[222:225], v[4:7]
	v_mfma_f32_16x16x32_bf16 v[0:3], v[190:193], v[222:225], v[0:3]
	s_setprio 0
	s_barrier
	s_add_i32 s59, 0, 0x18000
	v_add_u32_e32 v136, s59, v156
	s_add_i32 s60, 0, 0x1c000
	ds_read_b128 v[146:149], v136
	ds_read_b128 v[162:165], v136 offset:1024
	ds_read_b128 v[166:169], v136 offset:2048
	ds_read_b128 v[170:173], v136 offset:3072
	v_add_u32_e32 v136, s60, v156
	ds_read_b128 v[174:177], v136
	ds_read_b128 v[182:185], v136 offset:1024
	ds_read_b128 v[186:189], v136 offset:2048
	ds_read_b128 v[190:193], v136 offset:3072
	s_add_u32 s8, s8, 0x40000
	s_addc_u32 s9, s9, 0
	s_mov_b32 m0, s27
	v_lshl_add_u64 v[230:231], s[8:9], 0, v[128:129]
	ds_read_b128 v[194:197], v160 offset:32768
	ds_read_b128 v[198:201], v160 offset:33792
	ds_read_b128 v[202:205], v160 offset:34816
	ds_read_b128 v[206:209], v160 offset:35840
	ds_read_b128 v[210:213], v160 offset:36864
	ds_read_b128 v[214:217], v160 offset:37888
	ds_read_b128 v[218:221], v160 offset:38912
	ds_read_b128 v[222:225], v160 offset:39936
	global_load_lds_dwordx4 v[230:231], off
	v_lshl_add_u64 v[230:231], s[8:9], 0, v[132:133]
	s_mov_b32 m0, s28
	s_nop 0
	global_load_lds_dwordx4 v[230:231], off
	s_waitcnt vmcnt(8)
	s_waitcnt lgkmcnt(0)
	s_barrier
	s_setprio 1
	s_waitcnt lgkmcnt(0)
	v_mfma_f32_16x16x32_bf16 v[124:127], v[146:149], v[194:197], v[124:127]
	v_mfma_f32_16x16x32_bf16 v[120:123], v[166:169], v[194:197], v[120:123]
	v_mfma_f32_16x16x32_bf16 v[108:111], v[146:149], v[202:205], v[108:111]
	v_mfma_f32_16x16x32_bf16 v[104:107], v[166:169], v[202:205], v[104:107]
	v_mfma_f32_16x16x32_bf16 v[92:95], v[146:149], v[210:213], v[92:95]
	v_mfma_f32_16x16x32_bf16 v[88:91], v[166:169], v[210:213], v[88:91]
	v_mfma_f32_16x16x32_bf16 v[76:79], v[146:149], v[218:221], v[76:79]
	v_mfma_f32_16x16x32_bf16 v[72:75], v[166:169], v[218:221], v[72:75]
	v_mfma_f32_16x16x32_bf16 v[124:127], v[162:165], v[198:201], v[124:127]
	v_mfma_f32_16x16x32_bf16 v[120:123], v[170:173], v[198:201], v[120:123]
	v_mfma_f32_16x16x32_bf16 v[108:111], v[162:165], v[206:209], v[108:111]
	v_mfma_f32_16x16x32_bf16 v[104:107], v[170:173], v[206:209], v[104:107]
	v_mfma_f32_16x16x32_bf16 v[92:95], v[162:165], v[214:217], v[92:95]
	v_mfma_f32_16x16x32_bf16 v[88:91], v[170:173], v[214:217], v[88:91]
	v_mfma_f32_16x16x32_bf16 v[76:79], v[162:165], v[222:225], v[76:79]
	v_mfma_f32_16x16x32_bf16 v[72:75], v[170:173], v[222:225], v[72:75]
	v_mfma_f32_16x16x32_bf16 v[116:119], v[174:177], v[194:197], v[116:119]
	v_mfma_f32_16x16x32_bf16 v[112:115], v[186:189], v[194:197], v[112:115]
	v_mfma_f32_16x16x32_bf16 v[100:103], v[174:177], v[202:205], v[100:103]
	v_mfma_f32_16x16x32_bf16 v[96:99], v[186:189], v[202:205], v[96:99]
	v_mfma_f32_16x16x32_bf16 v[84:87], v[174:177], v[210:213], v[84:87]
	v_mfma_f32_16x16x32_bf16 v[80:83], v[186:189], v[210:213], v[80:83]
	v_mfma_f32_16x16x32_bf16 v[68:71], v[174:177], v[218:221], v[68:71]
	v_mfma_f32_16x16x32_bf16 v[64:67], v[186:189], v[218:221], v[64:67]
	v_mfma_f32_16x16x32_bf16 v[116:119], v[182:185], v[198:201], v[116:119]
	v_mfma_f32_16x16x32_bf16 v[112:115], v[190:193], v[198:201], v[112:115]
	v_mfma_f32_16x16x32_bf16 v[100:103], v[182:185], v[206:209], v[100:103]
	v_mfma_f32_16x16x32_bf16 v[96:99], v[190:193], v[206:209], v[96:99]
	v_mfma_f32_16x16x32_bf16 v[84:87], v[182:185], v[214:217], v[84:87]
	v_mfma_f32_16x16x32_bf16 v[80:83], v[190:193], v[214:217], v[80:83]
	v_mfma_f32_16x16x32_bf16 v[68:71], v[182:185], v[222:225], v[68:71]
	v_mfma_f32_16x16x32_bf16 v[64:67], v[190:193], v[222:225], v[64:67]
	s_setprio 0
	s_barrier
; #define PG8_STAGE(bufoff, gbase, voff) do { _Pragma("unroll") for (int _i = 0; _i < 2; ++_i) \
;         __builtin_amdgcn_global_load_lds((const unsigned*)((const char*)(gbase) + (voff)[_i]), (LAS unsigned*)(lds + (bufoff) + ldsw + _i * 8192), 16, 0, 0); } while (0)
; #define PG8_LDA(dst, b, h) do { _Pragma("unroll") for (int m = 0; m < 4; ++m) _Pragma("unroll") for (int k = 0; k < 2; ++k) dst[m][k] = *(const LAS bf16x8*)(lds + PG8_SA(b, h) + aoff + m * 2048 + k * 1024); } while (0)
; #define PG8_MMA(ai, bj, At, Bt) do { __builtin_amdgcn_s_setprio(1); _Pragma("unroll") for (int m = 0; m < 4; ++m) _Pragma("unroll") for (int n = 0; n < 2; ++n) _Pragma("unroll") for (int k = 0; k < 2; ++k) \
;         acc[ai][bj][m][n] = __builtin_amdgcn_mfma_f32_16x16x32_bf16(Bt[n][k], At[m][k], acc[ai][bj][m][n], 0, 0, 0); __builtin_amdgcn_s_setprio(0); } while (0)
; #define PG8_WAIT_V(n) asm volatile("s_waitcnt vmcnt(" #n ")" ::: "memory")
; #define PG8_WAIT_L(n) asm volatile("s_waitcnt lgkmcnt(" #n ")" ::: "memory")
; #define PG8_BAR __builtin_amdgcn_s_barrier()
; #define PG8_SCHED __builtin_amdgcn_sched_barrier(0)
; template <class Epi, class Sched, bool ALIGN_EPI = true>
; __device__ __forceinline__ void gemm_phase(LAS unsigned char* lds, const Gemm g, const Sched& S, const Epi& E) {
;     ...
;             PG8_LDA(At, 1, 1); PG8_STAGE(PG8_SB(1, 0), b3, voffB); PG8_STAGE(PG8_SB(1, 1), b3 + hsB, voffB); PG8_STAGE(PG8_SA(1, 0), a3, voffA);
;             PG8_WAIT_V(8); PG8_WAIT_L(0); PG8_BAR; PG8_MMA(1, 0, At, B0); PG8_MMA(1, 1, At, B1); PG8_BAR; PG8_SCHED;
;         }
	s_add_i32 s8, s59, s24
	v_lshl_add_u64 v[150:151], v[150:151], 0, s[12:13]
	s_mov_b32 m0, s8
	ds_read_b128 v[194:197], v160 offset:49152
	ds_read_b128 v[198:201], v160 offset:50176
	ds_read_b128 v[202:205], v160 offset:51200
	ds_read_b128 v[206:209], v160 offset:52224
	ds_read_b128 v[210:213], v160 offset:53248
	ds_read_b128 v[214:217], v160 offset:54272
	ds_read_b128 v[218:221], v160 offset:55296
	ds_read_b128 v[222:225], v160 offset:56320
	global_load_lds_dwordx4 v[150:151], off
	s_add_i32 m0, s8, 0x2000
	s_add_u32 s6, s6, 0x40080
	v_lshl_add_u64 v[150:151], v[178:179], 0, s[12:13]
	s_addc_u32 s7, s7, 0
	s_add_i32 s8, s60, s24
	global_load_lds_dwordx4 v[150:151], off
	v_lshl_add_u64 v[150:151], s[6:7], 0, v[130:131]
	s_mov_b32 m0, s8
	s_nop 0
	global_load_lds_dwordx4 v[150:151], off
	v_lshl_add_u64 v[150:151], s[6:7], 0, v[134:135]
	s_add_i32 m0, s8, 0x2000
	s_nop 0
	global_load_lds_dwordx4 v[150:151], off
	v_lshl_add_u64 v[150:151], v[226:227], 0, s[12:13]
	s_mov_b32 m0, s31
	s_nop 0
	global_load_lds_dwordx4 v[150:151], off
	v_lshl_add_u64 v[150:151], v[228:229], 0, s[12:13]
	s_mov_b32 m0, s34
	s_nop 0
	global_load_lds_dwordx4 v[150:151], off
	s_waitcnt vmcnt(8)
	s_waitcnt lgkmcnt(0)
	s_barrier
	s_setprio 1
	s_waitcnt lgkmcnt(0)
	v_mfma_f32_16x16x32_bf16 v[60:63], v[146:149], v[194:197], v[60:63]
	v_mfma_f32_16x16x32_bf16 v[56:59], v[166:169], v[194:197], v[56:59]
	v_mfma_f32_16x16x32_bf16 v[44:47], v[146:149], v[202:205], v[44:47]
	v_mfma_f32_16x16x32_bf16 v[40:43], v[166:169], v[202:205], v[40:43]
	v_mfma_f32_16x16x32_bf16 v[28:31], v[146:149], v[210:213], v[28:31]
	v_mfma_f32_16x16x32_bf16 v[24:27], v[166:169], v[210:213], v[24:27]
	v_mfma_f32_16x16x32_bf16 v[12:15], v[146:149], v[218:221], v[12:15]
	v_mfma_f32_16x16x32_bf16 v[8:11], v[166:169], v[218:221], v[8:11]
	v_mfma_f32_16x16x32_bf16 v[60:63], v[162:165], v[198:201], v[60:63]
	v_mfma_f32_16x16x32_bf16 v[56:59], v[170:173], v[198:201], v[56:59]
	v_mfma_f32_16x16x32_bf16 v[44:47], v[162:165], v[206:209], v[44:47]
	v_mfma_f32_16x16x32_bf16 v[40:43], v[170:173], v[206:209], v[40:43]
	v_mfma_f32_16x16x32_bf16 v[28:31], v[162:165], v[214:217], v[28:31]
	v_mfma_f32_16x16x32_bf16 v[24:27], v[170:173], v[214:217], v[24:27]
	v_mfma_f32_16x16x32_bf16 v[12:15], v[162:165], v[222:225], v[12:15]
	v_mfma_f32_16x16x32_bf16 v[8:11], v[170:173], v[222:225], v[8:11]
	v_mfma_f32_16x16x32_bf16 v[52:55], v[174:177], v[194:197], v[52:55]
	v_mfma_f32_16x16x32_bf16 v[48:51], v[186:189], v[194:197], v[48:51]
	v_mfma_f32_16x16x32_bf16 v[36:39], v[174:177], v[202:205], v[36:39]
	v_mfma_f32_16x16x32_bf16 v[32:35], v[186:189], v[202:205], v[32:35]
	v_mfma_f32_16x16x32_bf16 v[20:23], v[174:177], v[210:213], v[20:23]
	v_mfma_f32_16x16x32_bf16 v[16:19], v[186:189], v[210:213], v[16:19]
	v_mfma_f32_16x16x32_bf16 v[4:7], v[174:177], v[218:221], v[4:7]
	v_mfma_f32_16x16x32_bf16 v[0:3], v[186:189], v[218:221], v[0:3]
	v_mfma_f32_16x16x32_bf16 v[52:55], v[182:185], v[198:201], v[52:55]
	v_mfma_f32_16x16x32_bf16 v[48:51], v[190:193], v[198:201], v[48:51]
	v_mfma_f32_16x16x32_bf16 v[36:39], v[182:185], v[206:209], v[36:39]
	v_mfma_f32_16x16x32_bf16 v[32:35], v[190:193], v[206:209], v[32:35]
	v_mfma_f32_16x16x32_bf16 v[20:23], v[182:185], v[214:217], v[20:23]
	v_mfma_f32_16x16x32_bf16 v[16:19], v[190:193], v[214:217], v[16:19]
	v_mfma_f32_16x16x32_bf16 v[4:7], v[182:185], v[222:225], v[4:7]
	v_mfma_f32_16x16x32_bf16 v[0:3], v[190:193], v[222:225], v[0:3]
	s_setprio 0
	s_barrier
	s_add_i32 s58, s58, 2
	s_add_u32 s4, s4, 0x100
	s_addc_u32 s5, s5, 0
	s_add_u32 s23, s23, 0x100
	s_addc_u32 s33, s33, 0
	s_cmp_gt_u32 s58, 13
	s_cbranch_scc0 .LBB0_134
	s_and_b64 vcc, exec, s[14:15]
	s_cbranch_vccz .LBB0_137
	s_barrier

; __device__ __forceinline__ unsigned xb_add(unsigned* p, unsigned v) { return __hip_atomic_fetch_add(p, v, __ATOMIC_RELAXED, __HIP_MEMORY_SCOPE_AGENT); }
; __device__ __forceinline__ void xcd_barrier(const XcdBarrier& b) {
;     ...
;             __builtin_amdgcn_fence(__ATOMIC_ACQUIRE, "agent");
;             xb_add(&bar[XB_XGEN(b.x)], 1u);
;             asm volatile("s_waitcnt vmcnt(0)" ::: "memory");
.LBB0_300:
	s_or_b64 exec, exec, s[4:5]
	s_mov_b64 s[4:5], exec
	v_mbcnt_lo_u32_b32 v0, s4, 0
	v_mbcnt_hi_u32_b32 v0, s5, v0
	v_cmp_eq_u32_e32 vcc, 0, v0
	s_waitcnt vmcnt(0)
	buffer_inv sc1
	s_and_saveexec_b64 s[6:7], vcc
	s_cbranch_execz .LBB0_302
	s_bcnt1_i32_b64 s4, s[4:5]
.LBB0_302:
	s_or_b64 exec, exec, s[6:7]
	s_waitcnt vmcnt(0)

; __device__ __forceinline__ unsigned xb_add(unsigned* p, unsigned v) { return __hip_atomic_fetch_add(p, v, __ATOMIC_RELAXED, __HIP_MEMORY_SCOPE_AGENT); }
; __device__ __forceinline__ void xcd_barrier(const XcdBarrier& b) {
;     ...
;             __builtin_amdgcn_fence(__ATOMIC_ACQUIRE, "agent");
;             xb_add(&bar[XB_XGEN(b.x)], 1u);
;             asm volatile("s_waitcnt vmcnt(0)" ::: "memory");
.LBB0_616:
	s_or_b64 exec, exec, s[4:5]
	s_mov_b64 s[4:5], exec
	v_mbcnt_lo_u32_b32 v0, s4, 0
	v_mbcnt_hi_u32_b32 v0, s5, v0
	v_cmp_eq_u32_e32 vcc, 0, v0
	s_waitcnt vmcnt(0)
	buffer_inv sc1
	s_and_saveexec_b64 s[6:7], vcc
	s_cbranch_execz .LBB0_618
	s_bcnt1_i32_b64 s4, s[4:5]
.LBB0_618:
	s_or_b64 exec, exec, s[6:7]
	s_waitcnt vmcnt(0)

; __device__ __forceinline__ unsigned xb_ld(unsigned* p)              { return __hip_atomic_load(p, __ATOMIC_RELAXED, __HIP_MEMORY_SCOPE_AGENT); }
; __device__ __forceinline__ unsigned xb_add(unsigned* p, unsigned v) { return __hip_atomic_fetch_add(p, v, __ATOMIC_RELAXED, __HIP_MEMORY_SCOPE_AGENT); }
; #define XB_SPIN(cond, bar) do { unsigned _sp = 0; while (cond) { __builtin_amdgcn_s_sleep(1); \
;     if ((++_sp & 255u) == 0u) { if (xb_ld(&(bar)[XB_TMO])) break; if (_sp > XB_SPIN_CAP) { atomicAdd(&(bar)[XB_TMO], 1u); break; } } } } while (0)
; __device__ __forceinline__ void xcd_barrier(const XcdBarrier& b) {
;     ...
;         const unsigned old = xb_add(&bar[XB_XSUB(b.x)], 1u);
;         const unsigned gen = old / nloc;
;         if (old + 1u == (gen + 1u) * nloc) {
;             __builtin_amdgcn_fence(__ATOMIC_RELEASE, "agent");
;             asm volatile("s_waitcnt vmcnt(0)" ::: "memory");
;             const unsigned og = xb_add(&bar[XB_TOP], 1u);
;             const unsigned tg = og / nx;
;             if (og + 1u == (tg + 1u) * nx) xb_add(&bar[XB_TOPGEN], 1u);
;             else XB_SPIN(xb_ld(&bar[XB_TOPGEN]) == tg, bar);
;             __builtin_amdgcn_fence(__ATOMIC_ACQUIRE, "agent");
;             xb_add(&bar[XB_XGEN(b.x)], 1u);
;             asm volatile("s_waitcnt vmcnt(0)" ::: "memory");
;         } else {
;             XB_SPIN(xb_ld(&bar[XB_XGEN(b.x)]) == gen, bar);
.LBB0_646:
	s_or_b64 exec, exec, s[8:9]
	v_cvt_f32_u32_e32 v4, v2
	s_waitcnt vmcnt(0)
	v_readfirstlane_b32 s6, v3
	v_sub_u32_e32 v3, 0, v2
	v_rcp_iflag_f32_e32 v4, v4
	v_add_u32_e32 v5, s6, v1
	v_mul_f32_e32 v4, 0x4f7ffffe, v4
	v_cvt_u32_f32_e32 v4, v4
	v_mul_lo_u32 v1, v3, v4
	v_mul_hi_u32 v1, v4, v1
	v_add_u32_e32 v1, v4, v1
	v_mul_hi_u32 v1, v5, v1
	v_mul_lo_u32 v3, v1, v2
	v_sub_u32_e32 v3, v5, v3
	v_add_u32_e32 v4, 1, v1
	v_cmp_ge_u32_e32 vcc, v3, v2
	s_nop 1
	v_cndmask_b32_e32 v1, v1, v4, vcc
	v_sub_u32_e32 v4, v3, v2
	v_cndmask_b32_e32 v3, v3, v4, vcc
	v_add_u32_e32 v4, 1, v1
	v_cmp_ge_u32_e32 vcc, v3, v2
	v_add_u32_e32 v3, 1, v5
	s_nop 0
	v_cndmask_b32_e32 v1, v1, v4, vcc
	v_mul_lo_u32 v4, v2, v1
	v_add_u32_e32 v2, v4, v2
	v_cmp_ne_u32_e32 vcc, v3, v2
	s_and_saveexec_b64 s[6:7], vcc
	s_xor_b64 s[6:7], exec, s[6:7]
	s_cbranch_execz .LBB0_660
	s_waitcnt lgkmcnt(0)
	v_readlane_b32 s10, v237, 8
	v_readlane_b32 s11, v237, 9
	v_mov_b32_e32 v0, 0
	s_add_u32 s10, s10, 0x3500
	s_addc_u32 s11, s11, 0
	global_load_dword v0, v0, s[10:11] sc1
	s_waitcnt vmcnt(0)
	v_cmp_eq_u32_e32 vcc, v0, v1
	s_and_saveexec_b64 s[8:9], vcc
	s_cbranch_execz .LBB0_659
	s_mov_b32 s22, 1
	s_mov_b64 s[12:13], 0
	v_mov_b32_e32 v0, 0
	s_branch .LBB0_650

; __device__ __forceinline__ unsigned xb_add(unsigned* p, unsigned v) { return __hip_atomic_fetch_add(p, v, __ATOMIC_RELAXED, __HIP_MEMORY_SCOPE_AGENT); }
; __device__ __forceinline__ void xcd_barrier(const XcdBarrier& b) {
;     ...
;             __builtin_amdgcn_fence(__ATOMIC_ACQUIRE, "agent");
;             xb_add(&bar[XB_XGEN(b.x)], 1u);
;             asm volatile("s_waitcnt vmcnt(0)" ::: "memory");
.LBB0_677:
	s_or_b64 exec, exec, s[6:7]
	s_mov_b64 s[6:7], exec
	v_mbcnt_lo_u32_b32 v0, s6, 0
	v_mbcnt_hi_u32_b32 v0, s7, v0
	v_cmp_eq_u32_e32 vcc, 0, v0
	s_waitcnt vmcnt(0)
	buffer_inv sc1
	s_and_saveexec_b64 s[8:9], vcc
	s_cbranch_execz .LBB0_679
	s_bcnt1_i32_b64 s6, s[6:7]
.LBB0_679:
	s_or_b64 exec, exec, s[8:9]
	s_waitcnt vmcnt(0)

; #define PG8_STAGE(bufoff, gbase, voff) do { _Pragma("unroll") for (int _i = 0; _i < 2; ++_i) \
;         __builtin_amdgcn_global_load_lds((const unsigned*)((const char*)(gbase) + (voff)[_i]), (LAS unsigned*)(lds + (bufoff) + ldsw + _i * 8192), 16, 0, 0); } while (0)
; #define PG8_LDA(dst, b, h) do { _Pragma("unroll") for (int m = 0; m < 4; ++m) _Pragma("unroll") for (int k = 0; k < 2; ++k) dst[m][k] = *(const LAS bf16x8*)(lds + PG8_SA(b, h) + aoff + m * 2048 + k * 1024); } while (0)
; #define PG8_LDB(dst, b, h) do { _Pragma("unroll") for (int n = 0; n < 2; ++n) _Pragma("unroll") for (int k = 0; k < 2; ++k) dst[n][k] = *(const LAS bf16x8*)(lds + PG8_SB(b, h) + boff + n * 2048 + k * 1024); } while (0)
; #define PG8_MMA(ai, bj, At, Bt) do { __builtin_amdgcn_s_setprio(1); _Pragma("unroll") for (int m = 0; m < 4; ++m) _Pragma("unroll") for (int n = 0; n < 2; ++n) _Pragma("unroll") for (int k = 0; k < 2; ++k) \
;         acc[ai][bj][m][n] = __builtin_amdgcn_mfma_f32_16x16x32_bf16(Bt[n][k], At[m][k], acc[ai][bj][m][n], 0, 0, 0); __builtin_amdgcn_s_setprio(0); } while (0)
; #define PG8_WAIT_V(n) asm volatile("s_waitcnt vmcnt(" #n ")" ::: "memory")
; #define PG8_WAIT_L(n) asm volatile("s_waitcnt lgkmcnt(" #n ")" ::: "memory")
; #define PG8_BAR __builtin_amdgcn_s_barrier()
; #define PG8_SCHED __builtin_amdgcn_sched_barrier(0)
; template <class Epi, class Sched, bool ALIGN_EPI = true>
; __device__ __forceinline__ void gemm_phase(LAS unsigned char* lds, const Gemm g, const Sched& S, const Epi& E) {
;     ...
;             const bool last = (t == nt - 2);
;             const char* a1 = cA + (size_t)(t + 1) * kstep;
;             const char* a2 = last ? nA : cA + (size_t)(t + 2) * kstep; const char* b2 = last ? nB : cB + (size_t)(t + 2) * kstep;
;             const char* a3 = a2 + kstep; const char* b3 = b2 + kstep;
;             PG8_LDB(B0, 0, 0); PG8_LDB(B1, 0, 1); PG8_SCHED; PG8_LDA(At, 0, 0); PG8_STAGE(PG8_SA(1, 1), a1 + hsA, voffA);
;             PG8_WAIT_V(8); PG8_WAIT_L(0); PG8_BAR; PG8_MMA(0, 0, At, B0); PG8_MMA(0, 1, At, B1); PG8_BAR; PG8_SCHED;
;             PG8_LDA(At, 0, 1); PG8_STAGE(PG8_SB(0, 0), b2, voffB); PG8_STAGE(PG8_SB(0, 1), b2 + hsB, voffB); PG8_STAGE(PG8_SA(0, 0), a2, voffA);
;             PG8_WAIT_V(8); PG8_WAIT_L(0); PG8_BAR; PG8_MMA(1, 0, At, B0); PG8_MMA(1, 1, At, B1); PG8_BAR; PG8_SCHED;
.LBB0_704:
	ds_read_b128 v[144:147], v156
	ds_read_b128 v[148:151], v156 offset:1024
	ds_read_b128 v[160:163], v156 offset:2048
	ds_read_b128 v[164:167], v156 offset:3072
	ds_read_b128 v[168:171], v157
	ds_read_b128 v[172:175], v157 offset:1024
	ds_read_b128 v[176:179], v157 offset:2048
	ds_read_b128 v[182:185], v157 offset:3072
	s_add_u32 s38, s36, 0xfff80080
	s_addc_u32 s39, s37, -1
	s_cmp_eq_u32 s57, 28
	s_cselect_b32 s41, s9, s39
	s_cselect_b32 s40, s27, s38
	s_cselect_b32 s39, s25, s56
	s_cselect_b32 s38, s35, s55
	v_lshl_add_u64 v[218:219], s[36:37], 0, v[136:137]
	s_add_i32 m0, s42, 0xc000
	ds_read_b128 v[186:189], v158
	ds_read_b128 v[190:193], v158 offset:1024
	ds_read_b128 v[194:197], v158 offset:2048
	ds_read_b128 v[198:201], v158 offset:3072
	ds_read_b128 v[202:205], v158 offset:4096
	ds_read_b128 v[206:209], v158 offset:5120
	ds_read_b128 v[210:213], v158 offset:6144
	ds_read_b128 v[214:217], v158 offset:7168
	global_load_lds_dwordx4 v[218:219], off
	v_lshl_add_u64 v[218:219], s[36:37], 0, v[138:139]
	s_add_i32 m0, s42, 0xe000
	s_nop 0
	global_load_lds_dwordx4 v[218:219], off
	s_waitcnt vmcnt(8)
	s_waitcnt lgkmcnt(0)
	s_barrier
	s_setprio 1
	s_waitcnt lgkmcnt(0)
	v_mfma_f32_16x16x32_bf16 v[124:127], v[144:147], v[186:189], v[124:127]
	v_mfma_f32_16x16x32_bf16 v[120:123], v[160:163], v[186:189], v[120:123]
	v_mfma_f32_16x16x32_bf16 v[112:115], v[144:147], v[194:197], v[112:115]
	v_mfma_f32_16x16x32_bf16 v[104:107], v[160:163], v[194:197], v[104:107]
	v_mfma_f32_16x16x32_bf16 v[96:99], v[144:147], v[202:205], v[96:99]
	v_mfma_f32_16x16x32_bf16 v[88:91], v[160:163], v[202:205], v[88:91]
	v_mfma_f32_16x16x32_bf16 v[80:83], v[144:147], v[210:213], v[80:83]
	v_mfma_f32_16x16x32_bf16 v[72:75], v[160:163], v[210:213], v[72:75]
	v_mfma_f32_16x16x32_bf16 v[124:127], v[148:151], v[190:193], v[124:127]
	v_mfma_f32_16x16x32_bf16 v[120:123], v[164:167], v[190:193], v[120:123]
	v_mfma_f32_16x16x32_bf16 v[112:115], v[148:151], v[198:201], v[112:115]
	v_mfma_f32_16x16x32_bf16 v[104:107], v[164:167], v[198:201], v[104:107]
	v_mfma_f32_16x16x32_bf16 v[96:99], v[148:151], v[206:209], v[96:99]
	v_mfma_f32_16x16x32_bf16 v[88:91], v[164:167], v[206:209], v[88:91]
	v_mfma_f32_16x16x32_bf16 v[80:83], v[148:151], v[214:217], v[80:83]
	v_mfma_f32_16x16x32_bf16 v[72:75], v[164:167], v[214:217], v[72:75]
	v_mfma_f32_16x16x32_bf16 v[116:119], v[168:171], v[186:189], v[116:119]
	v_mfma_f32_16x16x32_bf16 v[108:111], v[176:179], v[186:189], v[108:111]
	v_mfma_f32_16x16x32_bf16 v[100:103], v[168:171], v[194:197], v[100:103]
	v_mfma_f32_16x16x32_bf16 v[92:95], v[176:179], v[194:197], v[92:95]
	v_mfma_f32_16x16x32_bf16 v[84:87], v[168:171], v[202:205], v[84:87]
	v_mfma_f32_16x16x32_bf16 v[76:79], v[176:179], v[202:205], v[76:79]
	v_mfma_f32_16x16x32_bf16 v[68:71], v[168:171], v[210:213], v[68:71]
	v_mfma_f32_16x16x32_bf16 v[64:67], v[176:179], v[210:213], v[64:67]
	v_mfma_f32_16x16x32_bf16 v[116:119], v[172:175], v[190:193], v[116:119]
	v_mfma_f32_16x16x32_bf16 v[108:111], v[182:185], v[190:193], v[108:111]
	v_mfma_f32_16x16x32_bf16 v[100:103], v[172:175], v[198:201], v[100:103]
	v_mfma_f32_16x16x32_bf16 v[92:95], v[182:185], v[198:201], v[92:95]
	v_mfma_f32_16x16x32_bf16 v[84:87], v[172:175], v[206:209], v[84:87]
	v_mfma_f32_16x16x32_bf16 v[76:79], v[182:185], v[206:209], v[76:79]
	v_mfma_f32_16x16x32_bf16 v[68:71], v[172:175], v[214:217], v[68:71]
	v_mfma_f32_16x16x32_bf16 v[64:67], v[182:185], v[214:217], v[64:67]
	s_setprio 0
	s_barrier
	s_add_i32 s58, s53, s33
	v_lshl_add_u64 v[218:219], s[38:39], 0, v[130:131]
	s_mov_b32 m0, s58
	ds_read_b128 v[186:189], v158 offset:16384
	ds_read_b128 v[190:193], v158 offset:17408
	ds_read_b128 v[194:197], v158 offset:18432
	ds_read_b128 v[198:201], v158 offset:19456
	ds_read_b128 v[202:205], v158 offset:20480
	ds_read_b128 v[206:209], v158 offset:21504
	ds_read_b128 v[210:213], v158 offset:22528
	ds_read_b128 v[214:217], v158 offset:23552
	global_load_lds_dwordx4 v[218:219], off
	s_add_i32 m0, s58, 0x2000
	s_add_u32 s58, s38, 0x80000
	v_lshl_add_u64 v[220:221], s[38:39], 0, v[134:135]
	s_addc_u32 s59, s39, 0
	s_add_i32 s60, s54, s33
	global_load_lds_dwordx4 v[220:221], off
	v_lshl_add_u64 v[222:223], s[58:59], 0, v[130:131]
	s_mov_b32 m0, s60
	v_lshl_add_u64 v[224:225], s[40:41], 0, v[132:133]
	global_load_lds_dwordx4 v[222:223], off
	v_lshl_add_u64 v[222:223], s[58:59], 0, v[134:135]
	s_add_i32 m0, s60, 0x2000
	s_nop 0
	global_load_lds_dwordx4 v[222:223], off
	v_lshl_add_u64 v[222:223], s[40:41], 0, v[128:129]
	s_mov_b32 m0, s42
	s_nop 0
	global_load_lds_dwordx4 v[222:223], off
	s_mov_b32 m0, s43
	s_nop 0
	global_load_lds_dwordx4 v[224:225], off
	s_waitcnt vmcnt(8)
	s_waitcnt lgkmcnt(0)
	s_barrier
; #define PG8_STAGE(bufoff, gbase, voff) do { _Pragma("unroll") for (int _i = 0; _i < 2; ++_i) \
;         __builtin_amdgcn_global_load_lds((const unsigned*)((const char*)(gbase) + (voff)[_i]), (LAS unsigned*)(lds + (bufoff) + ldsw + _i * 8192), 16, 0, 0); } while (0)
; #define PG8_LDA(dst, b, h) do { _Pragma("unroll") for (int m = 0; m < 4; ++m) _Pragma("unroll") for (int k = 0; k < 2; ++k) dst[m][k] = *(const LAS bf16x8*)(lds + PG8_SA(b, h) + aoff + m * 2048 + k * 1024); } while (0)
; #define PG8_LDB(dst, b, h) do { _Pragma("unroll") for (int n = 0; n < 2; ++n) _Pragma("unroll") for (int k = 0; k < 2; ++k) dst[n][k] = *(const LAS bf16x8*)(lds + PG8_SB(b, h) + boff + n * 2048 + k * 1024); } while (0)
; #define PG8_MMA(ai, bj, At, Bt) do { __builtin_amdgcn_s_setprio(1); _Pragma("unroll") for (int m = 0; m < 4; ++m) _Pragma("unroll") for (int n = 0; n < 2; ++n) _Pragma("unroll") for (int k = 0; k < 2; ++k) \
;         acc[ai][bj][m][n] = __builtin_amdgcn_mfma_f32_16x16x32_bf16(Bt[n][k], At[m][k], acc[ai][bj][m][n], 0, 0, 0); __builtin_amdgcn_s_setprio(0); } while (0)
; #define PG8_WAIT_V(n) asm volatile("s_waitcnt vmcnt(" #n ")" ::: "memory")
; #define PG8_WAIT_L(n) asm volatile("s_waitcnt lgkmcnt(" #n ")" ::: "memory")
; #define PG8_BAR __builtin_amdgcn_s_barrier()
; #define PG8_SCHED __builtin_amdgcn_sched_barrier(0)
; template <class Epi, class Sched, bool ALIGN_EPI = true>
; __device__ __forceinline__ void gemm_phase(LAS unsigned char* lds, const Gemm g, const Sched& S, const Epi& E) {
;     ...
;             PG8_WAIT_V(8); PG8_WAIT_L(0); PG8_BAR; PG8_MMA(1, 0, At, B0); PG8_MMA(1, 1, At, B1); PG8_BAR; PG8_SCHED;
;             PG8_LDB(B0, 1, 0); PG8_LDB(B1, 1, 1); PG8_SCHED; PG8_LDA(At, 1, 0); PG8_STAGE(PG8_SA(0, 1), a2 + hsA, voffA);
;             PG8_WAIT_V(8); PG8_WAIT_L(0); PG8_BAR; PG8_MMA(0, 0, At, B0); PG8_MMA(0, 1, At, B1); PG8_BAR; PG8_SCHED;
	s_setprio 1
	s_waitcnt lgkmcnt(0)
	v_mfma_f32_16x16x32_bf16 v[60:63], v[144:147], v[186:189], v[60:63]
	v_mfma_f32_16x16x32_bf16 v[56:59], v[160:163], v[186:189], v[56:59]
	v_mfma_f32_16x16x32_bf16 v[48:51], v[144:147], v[194:197], v[48:51]
	v_mfma_f32_16x16x32_bf16 v[40:43], v[160:163], v[194:197], v[40:43]
	v_mfma_f32_16x16x32_bf16 v[32:35], v[144:147], v[202:205], v[32:35]
	v_mfma_f32_16x16x32_bf16 v[24:27], v[160:163], v[202:205], v[24:27]
	v_mfma_f32_16x16x32_bf16 v[16:19], v[144:147], v[210:213], v[16:19]
	v_mfma_f32_16x16x32_bf16 v[8:11], v[160:163], v[210:213], v[8:11]
	v_mfma_f32_16x16x32_bf16 v[60:63], v[148:151], v[190:193], v[60:63]
	v_mfma_f32_16x16x32_bf16 v[56:59], v[164:167], v[190:193], v[56:59]
	v_mfma_f32_16x16x32_bf16 v[48:51], v[148:151], v[198:201], v[48:51]
	v_mfma_f32_16x16x32_bf16 v[40:43], v[164:167], v[198:201], v[40:43]
	v_mfma_f32_16x16x32_bf16 v[32:35], v[148:151], v[206:209], v[32:35]
	v_mfma_f32_16x16x32_bf16 v[24:27], v[164:167], v[206:209], v[24:27]
	v_mfma_f32_16x16x32_bf16 v[16:19], v[148:151], v[214:217], v[16:19]
	v_mfma_f32_16x16x32_bf16 v[8:11], v[164:167], v[214:217], v[8:11]
	v_mfma_f32_16x16x32_bf16 v[52:55], v[168:171], v[186:189], v[52:55]
	v_mfma_f32_16x16x32_bf16 v[44:47], v[176:179], v[186:189], v[44:47]
	v_mfma_f32_16x16x32_bf16 v[36:39], v[168:171], v[194:197], v[36:39]
	v_mfma_f32_16x16x32_bf16 v[28:31], v[176:179], v[194:197], v[28:31]
	v_mfma_f32_16x16x32_bf16 v[20:23], v[168:171], v[202:205], v[20:23]
	v_mfma_f32_16x16x32_bf16 v[12:15], v[176:179], v[202:205], v[12:15]
	v_mfma_f32_16x16x32_bf16 v[4:7], v[168:171], v[210:213], v[4:7]
	v_mfma_f32_16x16x32_bf16 v[0:3], v[176:179], v[210:213], v[0:3]
	v_mfma_f32_16x16x32_bf16 v[52:55], v[172:175], v[190:193], v[52:55]
	v_mfma_f32_16x16x32_bf16 v[44:47], v[182:185], v[190:193], v[44:47]
	v_mfma_f32_16x16x32_bf16 v[36:39], v[172:175], v[198:201], v[36:39]
	v_mfma_f32_16x16x32_bf16 v[28:31], v[182:185], v[198:201], v[28:31]
	v_mfma_f32_16x16x32_bf16 v[20:23], v[172:175], v[206:209], v[20:23]
	v_mfma_f32_16x16x32_bf16 v[12:15], v[182:185], v[206:209], v[12:15]
	v_mfma_f32_16x16x32_bf16 v[4:7], v[172:175], v[214:217], v[4:7]
	v_mfma_f32_16x16x32_bf16 v[0:3], v[182:185], v[214:217], v[0:3]
	s_setprio 0
	s_barrier
	s_add_i32 s58, 0, 0x18000
	v_add_u32_e32 v159, s58, v154
	s_add_i32 s59, 0, 0x1c000
	ds_read_b128 v[144:147], v159
	ds_read_b128 v[148:151], v159 offset:1024
	ds_read_b128 v[160:163], v159 offset:2048
	ds_read_b128 v[164:167], v159 offset:3072
	v_add_u32_e32 v159, s59, v154
	ds_read_b128 v[168:171], v159
	ds_read_b128 v[172:175], v159 offset:1024
	ds_read_b128 v[176:179], v159 offset:2048
	ds_read_b128 v[182:185], v159 offset:3072
	s_add_u32 s40, s40, 0x80000
	s_addc_u32 s41, s41, 0
	s_mov_b32 m0, s44
	v_lshl_add_u64 v[226:227], s[40:41], 0, v[128:129]
	ds_read_b128 v[186:189], v158 offset:32768
	ds_read_b128 v[190:193], v158 offset:33792
	ds_read_b128 v[194:197], v158 offset:34816
	ds_read_b128 v[198:201], v158 offset:35840
	ds_read_b128 v[202:205], v158 offset:36864
	ds_read_b128 v[206:209], v158 offset:37888
	ds_read_b128 v[210:213], v158 offset:38912
	ds_read_b128 v[214:217], v158 offset:39936
	global_load_lds_dwordx4 v[226:227], off
	v_lshl_add_u64 v[226:227], s[40:41], 0, v[132:133]
	s_mov_b32 m0, s45
	s_nop 0
	global_load_lds_dwordx4 v[226:227], off
	s_waitcnt vmcnt(8)
	s_waitcnt lgkmcnt(0)
	s_barrier
	s_setprio 1
	s_waitcnt lgkmcnt(0)
	v_mfma_f32_16x16x32_bf16 v[124:127], v[144:147], v[186:189], v[124:127]
	v_mfma_f32_16x16x32_bf16 v[120:123], v[160:163], v[186:189], v[120:123]
	v_mfma_f32_16x16x32_bf16 v[112:115], v[144:147], v[194:197], v[112:115]
	v_mfma_f32_16x16x32_bf16 v[104:107], v[160:163], v[194:197], v[104:107]
	v_mfma_f32_16x16x32_bf16 v[96:99], v[144:147], v[202:205], v[96:99]
	v_mfma_f32_16x16x32_bf16 v[88:91], v[160:163], v[202:205], v[88:91]
	v_mfma_f32_16x16x32_bf16 v[80:83], v[144:147], v[210:213], v[80:83]
	v_mfma_f32_16x16x32_bf16 v[72:75], v[160:163], v[210:213], v[72:75]
	v_mfma_f32_16x16x32_bf16 v[124:127], v[148:151], v[190:193], v[124:127]
	v_mfma_f32_16x16x32_bf16 v[120:123], v[164:167], v[190:193], v[120:123]
	v_mfma_f32_16x16x32_bf16 v[112:115], v[148:151], v[198:201], v[112:115]
	v_mfma_f32_16x16x32_bf16 v[104:107], v[164:167], v[198:201], v[104:107]
	v_mfma_f32_16x16x32_bf16 v[96:99], v[148:151], v[206:209], v[96:99]
	v_mfma_f32_16x16x32_bf16 v[88:91], v[164:167], v[206:209], v[88:91]
	v_mfma_f32_16x16x32_bf16 v[80:83], v[148:151], v[214:217], v[80:83]
	v_mfma_f32_16x16x32_bf16 v[72:75], v[164:167], v[214:217], v[72:75]
	v_mfma_f32_16x16x32_bf16 v[116:119], v[168:171], v[186:189], v[116:119]
	v_mfma_f32_16x16x32_bf16 v[108:111], v[176:179], v[186:189], v[108:111]
	v_mfma_f32_16x16x32_bf16 v[100:103], v[168:171], v[194:197], v[100:103]
	v_mfma_f32_16x16x32_bf16 v[92:95], v[176:179], v[194:197], v[92:95]
	v_mfma_f32_16x16x32_bf16 v[84:87], v[168:171], v[202:205], v[84:87]
	v_mfma_f32_16x16x32_bf16 v[76:79], v[176:179], v[202:205], v[76:79]
	v_mfma_f32_16x16x32_bf16 v[68:71], v[168:171], v[210:213], v[68:71]
	v_mfma_f32_16x16x32_bf16 v[64:67], v[176:179], v[210:213], v[64:67]
	v_mfma_f32_16x16x32_bf16 v[116:119], v[172:175], v[190:193], v[116:119]
	v_mfma_f32_16x16x32_bf16 v[108:111], v[182:185], v[190:193], v[108:111]
	v_mfma_f32_16x16x32_bf16 v[100:103], v[172:175], v[198:201], v[100:103]
	v_mfma_f32_16x16x32_bf16 v[92:95], v[182:185], v[198:201], v[92:95]
	v_mfma_f32_16x16x32_bf16 v[84:87], v[172:175], v[206:209], v[84:87]
	v_mfma_f32_16x16x32_bf16 v[76:79], v[182:185], v[206:209], v[76:79]
	v_mfma_f32_16x16x32_bf16 v[68:71], v[172:175], v[214:217], v[68:71]
	v_mfma_f32_16x16x32_bf16 v[64:67], v[182:185], v[214:217], v[64:67]
	s_setprio 0
	s_barrier
; #define PG8_STAGE(bufoff, gbase, voff) do { _Pragma("unroll") for (int _i = 0; _i < 2; ++_i) \
;         __builtin_amdgcn_global_load_lds((const unsigned*)((const char*)(gbase) + (voff)[_i]), (LAS unsigned*)(lds + (bufoff) + ldsw + _i * 8192), 16, 0, 0); } while (0)
; #define PG8_LDA(dst, b, h) do { _Pragma("unroll") for (int m = 0; m < 4; ++m) _Pragma("unroll") for (int k = 0; k < 2; ++k) dst[m][k] = *(const LAS bf16x8*)(lds + PG8_SA(b, h) + aoff + m * 2048 + k * 1024); } while (0)
; #define PG8_MMA(ai, bj, At, Bt) do { __builtin_amdgcn_s_setprio(1); _Pragma("unroll") for (int m = 0; m < 4; ++m) _Pragma("unroll") for (int n = 0; n < 2; ++n) _Pragma("unroll") for (int k = 0; k < 2; ++k) \
;         acc[ai][bj][m][n] = __builtin_amdgcn_mfma_f32_16x16x32_bf16(Bt[n][k], At[m][k], acc[ai][bj][m][n], 0, 0, 0); __builtin_amdgcn_s_setprio(0); } while (0)
; #define PG8_WAIT_V(n) asm volatile("s_waitcnt vmcnt(" #n ")" ::: "memory")
; #define PG8_WAIT_L(n) asm volatile("s_waitcnt lgkmcnt(" #n ")" ::: "memory")
; #define PG8_BAR __builtin_amdgcn_s_barrier()
; #define PG8_SCHED __builtin_amdgcn_sched_barrier(0)
; template <class Epi, class Sched, bool ALIGN_EPI = true>
; __device__ __forceinline__ void gemm_phase(LAS unsigned char* lds, const Gemm g, const Sched& S, const Epi& E) {
;     ...
;             PG8_LDA(At, 1, 1); PG8_STAGE(PG8_SB(1, 0), b3, voffB); PG8_STAGE(PG8_SB(1, 1), b3 + hsB, voffB); PG8_STAGE(PG8_SA(1, 0), a3, voffA);
;             PG8_WAIT_V(8); PG8_WAIT_L(0); PG8_BAR; PG8_MMA(1, 0, At, B0); PG8_MMA(1, 1, At, B1); PG8_BAR; PG8_SCHED;
;         }
	s_add_i32 s40, s58, s33
	v_lshl_add_u64 v[218:219], v[218:219], 0, s[12:13]
	s_mov_b32 m0, s40
	ds_read_b128 v[186:189], v158 offset:49152
	ds_read_b128 v[190:193], v158 offset:50176
	ds_read_b128 v[194:197], v158 offset:51200
	ds_read_b128 v[198:201], v158 offset:52224
	ds_read_b128 v[202:205], v158 offset:53248
	ds_read_b128 v[206:209], v158 offset:54272
	ds_read_b128 v[210:213], v158 offset:55296
	ds_read_b128 v[214:217], v158 offset:56320
	global_load_lds_dwordx4 v[218:219], off
	s_add_i32 m0, s40, 0x2000
	s_add_u32 s38, s38, 0x80080
	v_lshl_add_u64 v[218:219], v[220:221], 0, s[12:13]
	s_addc_u32 s39, s39, 0
	s_add_i32 s40, s59, s33
	global_load_lds_dwordx4 v[218:219], off
	v_lshl_add_u64 v[218:219], s[38:39], 0, v[130:131]
	s_mov_b32 m0, s40
	s_nop 0
	global_load_lds_dwordx4 v[218:219], off
	v_lshl_add_u64 v[218:219], s[38:39], 0, v[134:135]
	s_add_i32 m0, s40, 0x2000
	s_nop 0
	global_load_lds_dwordx4 v[218:219], off
	v_lshl_add_u64 v[218:219], v[222:223], 0, s[12:13]
	s_mov_b32 m0, s48
	s_nop 0
	global_load_lds_dwordx4 v[218:219], off
	v_lshl_add_u64 v[218:219], v[224:225], 0, s[12:13]
	s_mov_b32 m0, s49
	s_nop 0
	global_load_lds_dwordx4 v[218:219], off
	s_waitcnt vmcnt(8)
	s_waitcnt lgkmcnt(0)
	s_barrier
	s_setprio 1
	s_waitcnt lgkmcnt(0)
	v_mfma_f32_16x16x32_bf16 v[60:63], v[144:147], v[186:189], v[60:63]
	v_mfma_f32_16x16x32_bf16 v[56:59], v[160:163], v[186:189], v[56:59]
	v_mfma_f32_16x16x32_bf16 v[48:51], v[144:147], v[194:197], v[48:51]
	v_mfma_f32_16x16x32_bf16 v[40:43], v[160:163], v[194:197], v[40:43]
	v_mfma_f32_16x16x32_bf16 v[32:35], v[144:147], v[202:205], v[32:35]
	v_mfma_f32_16x16x32_bf16 v[24:27], v[160:163], v[202:205], v[24:27]
	v_mfma_f32_16x16x32_bf16 v[16:19], v[144:147], v[210:213], v[16:19]
	v_mfma_f32_16x16x32_bf16 v[8:11], v[160:163], v[210:213], v[8:11]
	v_mfma_f32_16x16x32_bf16 v[60:63], v[148:151], v[190:193], v[60:63]
	v_mfma_f32_16x16x32_bf16 v[56:59], v[164:167], v[190:193], v[56:59]
	v_mfma_f32_16x16x32_bf16 v[48:51], v[148:151], v[198:201], v[48:51]
	v_mfma_f32_16x16x32_bf16 v[40:43], v[164:167], v[198:201], v[40:43]
	v_mfma_f32_16x16x32_bf16 v[32:35], v[148:151], v[206:209], v[32:35]
	v_mfma_f32_16x16x32_bf16 v[24:27], v[164:167], v[206:209], v[24:27]
	v_mfma_f32_16x16x32_bf16 v[16:19], v[148:151], v[214:217], v[16:19]
	v_mfma_f32_16x16x32_bf16 v[8:11], v[164:167], v[214:217], v[8:11]
	v_mfma_f32_16x16x32_bf16 v[52:55], v[168:171], v[186:189], v[52:55]
	v_mfma_f32_16x16x32_bf16 v[44:47], v[176:179], v[186:189], v[44:47]
	v_mfma_f32_16x16x32_bf16 v[36:39], v[168:171], v[194:197], v[36:39]
	v_mfma_f32_16x16x32_bf16 v[28:31], v[176:179], v[194:197], v[28:31]
	v_mfma_f32_16x16x32_bf16 v[20:23], v[168:171], v[202:205], v[20:23]
	v_mfma_f32_16x16x32_bf16 v[12:15], v[176:179], v[202:205], v[12:15]
	v_mfma_f32_16x16x32_bf16 v[4:7], v[168:171], v[210:213], v[4:7]
	v_mfma_f32_16x16x32_bf16 v[0:3], v[176:179], v[210:213], v[0:3]
	v_mfma_f32_16x16x32_bf16 v[52:55], v[172:175], v[190:193], v[52:55]
	v_mfma_f32_16x16x32_bf16 v[44:47], v[182:185], v[190:193], v[44:47]
	v_mfma_f32_16x16x32_bf16 v[36:39], v[172:175], v[198:201], v[36:39]
	v_mfma_f32_16x16x32_bf16 v[28:31], v[182:185], v[198:201], v[28:31]
	v_mfma_f32_16x16x32_bf16 v[20:23], v[172:175], v[206:209], v[20:23]
	v_mfma_f32_16x16x32_bf16 v[12:15], v[182:185], v[206:209], v[12:15]
	v_mfma_f32_16x16x32_bf16 v[4:7], v[172:175], v[214:217], v[4:7]
	v_mfma_f32_16x16x32_bf16 v[0:3], v[182:185], v[214:217], v[0:3]
	s_setprio 0
	s_barrier
	s_add_i32 s57, s57, 2
	s_add_u32 s36, s36, 0x100
	s_addc_u32 s37, s37, 0
	s_add_u32 s55, s55, 0x100
	s_addc_u32 s56, s56, 0
	s_cmp_gt_u32 s57, 29
	s_cbranch_scc0 .LBB0_704
	s_and_b64 vcc, exec, s[14:15]
	s_cbranch_vccz .LBB0_707
	s_barrier

; __device__ __forceinline__ unsigned xb_ld(unsigned* p)              { return __hip_atomic_load(p, __ATOMIC_RELAXED, __HIP_MEMORY_SCOPE_AGENT); }
; __device__ __forceinline__ unsigned xb_add(unsigned* p, unsigned v) { return __hip_atomic_fetch_add(p, v, __ATOMIC_RELAXED, __HIP_MEMORY_SCOPE_AGENT); }
; #define XB_SPIN(cond, bar) do { unsigned _sp = 0; while (cond) { __builtin_amdgcn_s_sleep(1); \
;     if ((++_sp & 255u) == 0u) { if (xb_ld(&(bar)[XB_TMO])) break; if (_sp > XB_SPIN_CAP) { atomicAdd(&(bar)[XB_TMO], 1u); break; } } } } while (0)
; __device__ __forceinline__ void xcd_barrier(const XcdBarrier& b) {
;     ...
;         const unsigned old = xb_add(&bar[XB_XSUB(b.x)], 1u);
;         const unsigned gen = old / nloc;
;         if (old + 1u == (gen + 1u) * nloc) {
;             __builtin_amdgcn_fence(__ATOMIC_RELEASE, "agent");
;             asm volatile("s_waitcnt vmcnt(0)" ::: "memory");
;             const unsigned og = xb_add(&bar[XB_TOP], 1u);
;             const unsigned tg = og / nx;
;             if (og + 1u == (tg + 1u) * nx) xb_add(&bar[XB_TOPGEN], 1u);
;             else XB_SPIN(xb_ld(&bar[XB_TOPGEN]) == tg, bar);
;             __builtin_amdgcn_fence(__ATOMIC_ACQUIRE, "agent");
;             xb_add(&bar[XB_XGEN(b.x)], 1u);
;             asm volatile("s_waitcnt vmcnt(0)" ::: "memory");
;         } else {
;             XB_SPIN(xb_ld(&bar[XB_XGEN(b.x)]) == gen, bar);
.LBB0_761:
	s_or_b64 exec, exec, s[12:13]
	v_cvt_f32_u32_e32 v4, v2
	s_waitcnt vmcnt(0)
	v_readfirstlane_b32 s10, v3
	v_sub_u32_e32 v3, 0, v2
	v_rcp_iflag_f32_e32 v4, v4
	v_add_u32_e32 v5, s10, v1
	v_mul_f32_e32 v4, 0x4f7ffffe, v4
	v_cvt_u32_f32_e32 v4, v4
	v_mul_lo_u32 v1, v3, v4
	v_mul_hi_u32 v1, v4, v1
	v_add_u32_e32 v1, v4, v1
	v_mul_hi_u32 v1, v5, v1
	v_mul_lo_u32 v3, v1, v2
	v_sub_u32_e32 v3, v5, v3
	v_add_u32_e32 v4, 1, v1
	v_cmp_ge_u32_e32 vcc, v3, v2
	s_nop 1
	v_cndmask_b32_e32 v1, v1, v4, vcc
	v_sub_u32_e32 v4, v3, v2
	v_cndmask_b32_e32 v3, v3, v4, vcc
	v_add_u32_e32 v4, 1, v1
	v_cmp_ge_u32_e32 vcc, v3, v2
	v_add_u32_e32 v3, 1, v5
	s_nop 0
	v_cndmask_b32_e32 v1, v1, v4, vcc
	v_mul_lo_u32 v4, v2, v1
	v_add_u32_e32 v2, v4, v2
	v_cmp_ne_u32_e32 vcc, v3, v2
	s_and_saveexec_b64 s[10:11], vcc
	s_xor_b64 s[10:11], exec, s[10:11]
	s_cbranch_execz .LBB0_775
	s_waitcnt lgkmcnt(0)
	v_readlane_b32 s14, v237, 8
	v_readlane_b32 s15, v237, 9
	v_mov_b32_e32 v0, 0
	s_add_u32 s14, s14, 0x3500
	s_addc_u32 s15, s15, 0
	global_load_dword v0, v0, s[14:15] sc1
	s_waitcnt vmcnt(0)
	v_cmp_eq_u32_e32 vcc, v0, v1
	s_and_saveexec_b64 s[12:13], vcc
	s_cbranch_execz .LBB0_774
	s_mov_b32 s26, 1
	s_mov_b64 s[16:17], 0
	v_mov_b32_e32 v0, 0
	s_branch .LBB0_765

; __device__ __forceinline__ unsigned xb_add(unsigned* p, unsigned v) { return __hip_atomic_fetch_add(p, v, __ATOMIC_RELAXED, __HIP_MEMORY_SCOPE_AGENT); }
; __device__ __forceinline__ void xcd_barrier(const XcdBarrier& b) {
;     ...
;             __builtin_amdgcn_fence(__ATOMIC_ACQUIRE, "agent");
;             xb_add(&bar[XB_XGEN(b.x)], 1u);
;             asm volatile("s_waitcnt vmcnt(0)" ::: "memory");
.LBB0_792:
	s_or_b64 exec, exec, s[10:11]
	s_mov_b64 s[10:11], exec
	v_mbcnt_lo_u32_b32 v0, s10, 0
	v_mbcnt_hi_u32_b32 v0, s11, v0
	v_cmp_eq_u32_e32 vcc, 0, v0
	s_waitcnt vmcnt(0)
	buffer_inv sc1
	s_and_saveexec_b64 s[12:13], vcc
	s_cbranch_execz .LBB0_794
	s_bcnt1_i32_b64 s10, s[10:11]
.LBB0_794:
	s_or_b64 exec, exec, s[12:13]
	s_waitcnt vmcnt(0)

; __device__ __forceinline__ unsigned xb_ld(unsigned* p)              { return __hip_atomic_load(p, __ATOMIC_RELAXED, __HIP_MEMORY_SCOPE_AGENT); }
; __device__ __forceinline__ unsigned xb_add(unsigned* p, unsigned v) { return __hip_atomic_fetch_add(p, v, __ATOMIC_RELAXED, __HIP_MEMORY_SCOPE_AGENT); }
; #define XB_SPIN(cond, bar) do { unsigned _sp = 0; while (cond) { __builtin_amdgcn_s_sleep(1); \
;     if ((++_sp & 255u) == 0u) { if (xb_ld(&(bar)[XB_TMO])) break; if (_sp > XB_SPIN_CAP) { atomicAdd(&(bar)[XB_TMO], 1u); break; } } } } while (0)
; __device__ __forceinline__ void xcd_barrier(const XcdBarrier& b) {
;     ...
;         const unsigned old = xb_add(&bar[XB_XSUB(b.x)], 1u);
;         const unsigned gen = old / nloc;
;         if (old + 1u == (gen + 1u) * nloc) {
;             __builtin_amdgcn_fence(__ATOMIC_RELEASE, "agent");
;             asm volatile("s_waitcnt vmcnt(0)" ::: "memory");
;             const unsigned og = xb_add(&bar[XB_TOP], 1u);
;             const unsigned tg = og / nx;
;             if (og + 1u == (tg + 1u) * nx) xb_add(&bar[XB_TOPGEN], 1u);
;             else XB_SPIN(xb_ld(&bar[XB_TOPGEN]) == tg, bar);
;             __builtin_amdgcn_fence(__ATOMIC_ACQUIRE, "agent");
;             xb_add(&bar[XB_XGEN(b.x)], 1u);
;             asm volatile("s_waitcnt vmcnt(0)" ::: "memory");
;         } else {
;             XB_SPIN(xb_ld(&bar[XB_XGEN(b.x)]) == gen, bar);
.LBB0_826:
	s_or_b64 exec, exec, s[8:9]
	v_cvt_f32_u32_e32 v4, v2
	s_waitcnt vmcnt(0)
	v_readfirstlane_b32 s6, v3
	v_sub_u32_e32 v3, 0, v2
	v_rcp_iflag_f32_e32 v4, v4
	v_add_u32_e32 v5, s6, v1
	v_mul_f32_e32 v4, 0x4f7ffffe, v4
	v_cvt_u32_f32_e32 v4, v4
	v_mul_lo_u32 v1, v3, v4
	v_mul_hi_u32 v1, v4, v1
	v_add_u32_e32 v1, v4, v1
	v_mul_hi_u32 v1, v5, v1
	v_mul_lo_u32 v3, v1, v2
	v_sub_u32_e32 v3, v5, v3
	v_add_u32_e32 v4, 1, v1
	v_cmp_ge_u32_e32 vcc, v3, v2
	s_nop 1
	v_cndmask_b32_e32 v1, v1, v4, vcc
	v_sub_u32_e32 v4, v3, v2
	v_cndmask_b32_e32 v3, v3, v4, vcc
	v_add_u32_e32 v4, 1, v1
	v_cmp_ge_u32_e32 vcc, v3, v2
	v_add_u32_e32 v3, 1, v5
	s_nop 0
	v_cndmask_b32_e32 v1, v1, v4, vcc
	v_mul_lo_u32 v4, v2, v1
	v_add_u32_e32 v2, v4, v2
	v_cmp_ne_u32_e32 vcc, v3, v2
	s_and_saveexec_b64 s[6:7], vcc
	s_xor_b64 s[6:7], exec, s[6:7]
	s_cbranch_execz .LBB0_840
	s_waitcnt lgkmcnt(0)
	v_readlane_b32 s12, v237, 8
	v_readlane_b32 s13, v237, 9
	v_mov_b32_e32 v0, 0
	s_add_u32 s12, s12, 0x3500
	s_addc_u32 s13, s13, 0
	global_load_dword v0, v0, s[12:13] sc1
	s_waitcnt vmcnt(0)
	v_cmp_eq_u32_e32 vcc, v0, v1
	s_and_saveexec_b64 s[8:9], vcc
	s_cbranch_execz .LBB0_839
	s_mov_b32 s24, 1
	s_mov_b64 s[14:15], 0
	v_mov_b32_e32 v0, 0
	s_branch .LBB0_830

; __device__ __forceinline__ unsigned xb_add(unsigned* p, unsigned v) { return __hip_atomic_fetch_add(p, v, __ATOMIC_RELAXED, __HIP_MEMORY_SCOPE_AGENT); }
; __device__ __forceinline__ void xcd_barrier(const XcdBarrier& b) {
;     ...
;             __builtin_amdgcn_fence(__ATOMIC_ACQUIRE, "agent");
;             xb_add(&bar[XB_XGEN(b.x)], 1u);
;             asm volatile("s_waitcnt vmcnt(0)" ::: "memory");
.LBB0_857:
	s_or_b64 exec, exec, s[6:7]
	s_mov_b64 s[6:7], exec
	v_mbcnt_lo_u32_b32 v0, s6, 0
	v_mbcnt_hi_u32_b32 v0, s7, v0
	v_cmp_eq_u32_e32 vcc, 0, v0
	s_waitcnt vmcnt(0)
	buffer_inv sc1
	s_and_saveexec_b64 s[8:9], vcc
	s_cbranch_execz .LBB0_859
	s_bcnt1_i32_b64 s6, s[6:7]
.LBB0_859:
	s_or_b64 exec, exec, s[8:9]
	s_waitcnt vmcnt(0)

; #define PG8_STAGE(bufoff, gbase, voff) do { _Pragma("unroll") for (int _i = 0; _i < 2; ++_i) \
;         __builtin_amdgcn_global_load_lds((const unsigned*)((const char*)(gbase) + (voff)[_i]), (LAS unsigned*)(lds + (bufoff) + ldsw + _i * 8192), 16, 0, 0); } while (0)
; #define PG8_LDA(dst, b, h) do { _Pragma("unroll") for (int m = 0; m < 4; ++m) _Pragma("unroll") for (int k = 0; k < 2; ++k) dst[m][k] = *(const LAS bf16x8*)(lds + PG8_SA(b, h) + aoff + m * 2048 + k * 1024); } while (0)
; #define PG8_LDB(dst, b, h) do { _Pragma("unroll") for (int n = 0; n < 2; ++n) _Pragma("unroll") for (int k = 0; k < 2; ++k) dst[n][k] = *(const LAS bf16x8*)(lds + PG8_SB(b, h) + boff + n * 2048 + k * 1024); } while (0)
; #define PG8_MMA(ai, bj, At, Bt) do { __builtin_amdgcn_s_setprio(1); _Pragma("unroll") for (int m = 0; m < 4; ++m) _Pragma("unroll") for (int n = 0; n < 2; ++n) _Pragma("unroll") for (int k = 0; k < 2; ++k) \
;         acc[ai][bj][m][n] = __builtin_amdgcn_mfma_f32_16x16x32_bf16(Bt[n][k], At[m][k], acc[ai][bj][m][n], 0, 0, 0); __builtin_amdgcn_s_setprio(0); } while (0)
; #define PG8_WAIT_V(n) asm volatile("s_waitcnt vmcnt(" #n ")" ::: "memory")
; #define PG8_WAIT_L(n) asm volatile("s_waitcnt lgkmcnt(" #n ")" ::: "memory")
; #define PG8_BAR __builtin_amdgcn_s_barrier()
; #define PG8_SCHED __builtin_amdgcn_sched_barrier(0)
; template <class Epi, class Sched, bool ALIGN_EPI = true>
; __device__ __forceinline__ void gemm_phase(LAS unsigned char* lds, const Gemm g, const Sched& S, const Epi& E) {
;     ...
;             const bool last = (t == nt - 2);
;             const char* a1 = cA + (size_t)(t + 1) * kstep;
;             const char* a2 = last ? nA : cA + (size_t)(t + 2) * kstep; const char* b2 = last ? nB : cB + (size_t)(t + 2) * kstep;
;             const char* a3 = a2 + kstep; const char* b3 = b2 + kstep;
;             PG8_LDB(B0, 0, 0); PG8_LDB(B1, 0, 1); PG8_SCHED; PG8_LDA(At, 0, 0); PG8_STAGE(PG8_SA(1, 1), a1 + hsA, voffA);
;             PG8_WAIT_V(8); PG8_WAIT_L(0); PG8_BAR; PG8_MMA(0, 0, At, B0); PG8_MMA(0, 1, At, B1); PG8_BAR; PG8_SCHED;
;             PG8_LDA(At, 0, 1); PG8_STAGE(PG8_SB(0, 0), b2, voffB); PG8_STAGE(PG8_SB(0, 1), b2 + hsB, voffB); PG8_STAGE(PG8_SA(0, 0), a2, voffA);
;             PG8_WAIT_V(8); PG8_WAIT_L(0); PG8_BAR; PG8_MMA(1, 0, At, B0); PG8_MMA(1, 1, At, B1); PG8_BAR; PG8_SCHED;
.LBB0_881:
	ds_read_b128 v[116:119], v184
	ds_read_b128 v[120:123], v184 offset:1024
	ds_read_b128 v[128:131], v184 offset:2048
	ds_read_b128 v[132:135], v184 offset:3072
	ds_read_b128 v[144:147], v185
	ds_read_b128 v[148:151], v185 offset:1024
	ds_read_b128 v[170:173], v185 offset:2048
	ds_read_b128 v[174:177], v185 offset:3072
	s_add_u32 s26, s6, 0xfffc0080
	s_addc_u32 s27, s7, -1
	s_cmp_eq_u32 s35, 12
	s_cselect_b32 s29, s23, s27
	s_cselect_b32 s28, s22, s26
	s_cselect_b32 s27, s9, s34
	s_cselect_b32 s26, s21, s31
	v_lshl_add_u64 v[178:179], s[6:7], 0, v[162:163]
	s_add_i32 m0, s42, 0xc000
	ds_read_b128 v[188:191], v186
	ds_read_b128 v[192:195], v186 offset:1024
	ds_read_b128 v[196:199], v186 offset:2048
	ds_read_b128 v[200:203], v186 offset:3072
	ds_read_b128 v[204:207], v186 offset:4096
	ds_read_b128 v[208:211], v186 offset:5120
	ds_read_b128 v[212:215], v186 offset:6144
	ds_read_b128 v[216:219], v186 offset:7168
	global_load_lds_dwordx4 v[178:179], off
	v_lshl_add_u64 v[178:179], s[6:7], 0, v[164:165]
	s_add_i32 m0, s42, 0xe000
	s_nop 0
	global_load_lds_dwordx4 v[178:179], off
	s_waitcnt vmcnt(8)
	s_waitcnt lgkmcnt(0)
	s_barrier
	s_setprio 1
	s_waitcnt lgkmcnt(0)
	v_mfma_f32_16x16x32_bf16 v[140:143], v[116:119], v[188:191], v[140:143]
	v_mfma_f32_16x16x32_bf16 v[64:67], v[128:131], v[188:191], v[64:67]
	v_mfma_f32_16x16x32_bf16 v[124:127], v[116:119], v[196:199], v[124:127]
	v_mfma_f32_16x16x32_bf16 v[52:55], v[128:131], v[196:199], v[52:55]
	v_mfma_f32_16x16x32_bf16 v[108:111], v[116:119], v[204:207], v[108:111]
	v_mfma_f32_16x16x32_bf16 v[44:47], v[128:131], v[204:207], v[44:47]
	v_mfma_f32_16x16x32_bf16 v[100:103], v[116:119], v[212:215], v[100:103]
	v_mfma_f32_16x16x32_bf16 v[36:39], v[128:131], v[212:215], v[36:39]
	v_mfma_f32_16x16x32_bf16 v[140:143], v[120:123], v[192:195], v[140:143]
	v_mfma_f32_16x16x32_bf16 v[64:67], v[132:135], v[192:195], v[64:67]
	v_mfma_f32_16x16x32_bf16 v[124:127], v[120:123], v[200:203], v[124:127]
	v_mfma_f32_16x16x32_bf16 v[52:55], v[132:135], v[200:203], v[52:55]
	v_mfma_f32_16x16x32_bf16 v[108:111], v[120:123], v[208:211], v[108:111]
	v_mfma_f32_16x16x32_bf16 v[44:47], v[132:135], v[208:211], v[44:47]
	v_mfma_f32_16x16x32_bf16 v[100:103], v[120:123], v[216:219], v[100:103]
	v_mfma_f32_16x16x32_bf16 v[36:39], v[132:135], v[216:219], v[36:39]
	v_mfma_f32_16x16x32_bf16 v[136:139], v[144:147], v[188:191], v[136:139]
	v_mfma_f32_16x16x32_bf16 v[56:59], v[170:173], v[188:191], v[56:59]
	v_mfma_f32_16x16x32_bf16 v[112:115], v[144:147], v[196:199], v[112:115]
	v_mfma_f32_16x16x32_bf16 v[48:51], v[170:173], v[196:199], v[48:51]
	v_mfma_f32_16x16x32_bf16 v[104:107], v[144:147], v[204:207], v[104:107]
	v_mfma_f32_16x16x32_bf16 v[40:43], v[170:173], v[204:207], v[40:43]
	v_mfma_f32_16x16x32_bf16 v[96:99], v[144:147], v[212:215], v[96:99]
	v_mfma_f32_16x16x32_bf16 v[32:35], v[170:173], v[212:215], v[32:35]
	v_mfma_f32_16x16x32_bf16 v[136:139], v[148:151], v[192:195], v[136:139]
	v_mfma_f32_16x16x32_bf16 v[56:59], v[174:177], v[192:195], v[56:59]
	v_mfma_f32_16x16x32_bf16 v[112:115], v[148:151], v[200:203], v[112:115]
	v_mfma_f32_16x16x32_bf16 v[48:51], v[174:177], v[200:203], v[48:51]
	v_mfma_f32_16x16x32_bf16 v[104:107], v[148:151], v[208:211], v[104:107]
	v_mfma_f32_16x16x32_bf16 v[40:43], v[174:177], v[208:211], v[40:43]
	v_mfma_f32_16x16x32_bf16 v[96:99], v[148:151], v[216:219], v[96:99]
	v_mfma_f32_16x16x32_bf16 v[32:35], v[174:177], v[216:219], v[32:35]
	s_setprio 0
	s_barrier
	s_add_i32 s36, s62, s33
	v_lshl_add_u64 v[178:179], s[26:27], 0, v[156:157]
	s_mov_b32 m0, s36
	ds_read_b128 v[188:191], v186 offset:16384
	ds_read_b128 v[192:195], v186 offset:17408
	ds_read_b128 v[196:199], v186 offset:18432
	ds_read_b128 v[200:203], v186 offset:19456
	ds_read_b128 v[204:207], v186 offset:20480
	ds_read_b128 v[208:211], v186 offset:21504
	ds_read_b128 v[212:215], v186 offset:22528
	ds_read_b128 v[216:219], v186 offset:23552
	global_load_lds_dwordx4 v[178:179], off
	s_add_i32 m0, s36, 0x2000
	s_add_u32 s36, s26, 0x40000
	v_lshl_add_u64 v[220:221], s[26:27], 0, v[160:161]
	s_addc_u32 s37, s27, 0
	s_add_i32 s38, s63, s33
	global_load_lds_dwordx4 v[220:221], off
	v_lshl_add_u64 v[222:223], s[36:37], 0, v[156:157]
	s_mov_b32 m0, s38
	v_lshl_add_u64 v[224:225], s[28:29], 0, v[158:159]
	global_load_lds_dwordx4 v[222:223], off
	v_lshl_add_u64 v[222:223], s[36:37], 0, v[160:161]
	s_add_i32 m0, s38, 0x2000
	s_nop 0
	global_load_lds_dwordx4 v[222:223], off
	v_lshl_add_u64 v[222:223], s[28:29], 0, v[154:155]
	s_mov_b32 m0, s42
	s_nop 0
	global_load_lds_dwordx4 v[222:223], off
	s_mov_b32 m0, s43
	s_nop 0
	global_load_lds_dwordx4 v[224:225], off
	s_waitcnt vmcnt(8)
	s_waitcnt lgkmcnt(0)
	s_barrier
; #define PG8_STAGE(bufoff, gbase, voff) do { _Pragma("unroll") for (int _i = 0; _i < 2; ++_i) \
;         __builtin_amdgcn_global_load_lds((const unsigned*)((const char*)(gbase) + (voff)[_i]), (LAS unsigned*)(lds + (bufoff) + ldsw + _i * 8192), 16, 0, 0); } while (0)
; #define PG8_LDA(dst, b, h) do { _Pragma("unroll") for (int m = 0; m < 4; ++m) _Pragma("unroll") for (int k = 0; k < 2; ++k) dst[m][k] = *(const LAS bf16x8*)(lds + PG8_SA(b, h) + aoff + m * 2048 + k * 1024); } while (0)
; #define PG8_LDB(dst, b, h) do { _Pragma("unroll") for (int n = 0; n < 2; ++n) _Pragma("unroll") for (int k = 0; k < 2; ++k) dst[n][k] = *(const LAS bf16x8*)(lds + PG8_SB(b, h) + boff + n * 2048 + k * 1024); } while (0)
; #define PG8_MMA(ai, bj, At, Bt) do { __builtin_amdgcn_s_setprio(1); _Pragma("unroll") for (int m = 0; m < 4; ++m) _Pragma("unroll") for (int n = 0; n < 2; ++n) _Pragma("unroll") for (int k = 0; k < 2; ++k) \
;         acc[ai][bj][m][n] = __builtin_amdgcn_mfma_f32_16x16x32_bf16(Bt[n][k], At[m][k], acc[ai][bj][m][n], 0, 0, 0); __builtin_amdgcn_s_setprio(0); } while (0)
; #define PG8_WAIT_V(n) asm volatile("s_waitcnt vmcnt(" #n ")" ::: "memory")
; #define PG8_WAIT_L(n) asm volatile("s_waitcnt lgkmcnt(" #n ")" ::: "memory")
; #define PG8_BAR __builtin_amdgcn_s_barrier()
; #define PG8_SCHED __builtin_amdgcn_sched_barrier(0)
; template <class Epi, class Sched, bool ALIGN_EPI = true>
; __device__ __forceinline__ void gemm_phase(LAS unsigned char* lds, const Gemm g, const Sched& S, const Epi& E) {
;     ...
;             PG8_WAIT_V(8); PG8_WAIT_L(0); PG8_BAR; PG8_MMA(1, 0, At, B0); PG8_MMA(1, 1, At, B1); PG8_BAR; PG8_SCHED;
;             PG8_LDB(B0, 1, 0); PG8_LDB(B1, 1, 1); PG8_SCHED; PG8_LDA(At, 1, 0); PG8_STAGE(PG8_SA(0, 1), a2 + hsA, voffA);
;             PG8_WAIT_V(8); PG8_WAIT_L(0); PG8_BAR; PG8_MMA(0, 0, At, B0); PG8_MMA(0, 1, At, B1); PG8_BAR; PG8_SCHED;
	s_setprio 1
	s_waitcnt lgkmcnt(0)
	v_mfma_f32_16x16x32_bf16 v[92:95], v[116:119], v[188:191], v[92:95]
	v_mfma_f32_16x16x32_bf16 v[28:31], v[128:131], v[188:191], v[28:31]
	v_mfma_f32_16x16x32_bf16 v[84:87], v[116:119], v[196:199], v[84:87]
	v_mfma_f32_16x16x32_bf16 v[20:23], v[128:131], v[196:199], v[20:23]
	v_mfma_f32_16x16x32_bf16 v[76:79], v[116:119], v[204:207], v[76:79]
	v_mfma_f32_16x16x32_bf16 v[12:15], v[128:131], v[204:207], v[12:15]
	v_mfma_f32_16x16x32_bf16 v[68:71], v[116:119], v[212:215], v[68:71]
	v_mfma_f32_16x16x32_bf16 v[4:7], v[128:131], v[212:215], v[4:7]
	v_mfma_f32_16x16x32_bf16 v[92:95], v[120:123], v[192:195], v[92:95]
	v_mfma_f32_16x16x32_bf16 v[28:31], v[132:135], v[192:195], v[28:31]
	v_mfma_f32_16x16x32_bf16 v[84:87], v[120:123], v[200:203], v[84:87]
	v_mfma_f32_16x16x32_bf16 v[20:23], v[132:135], v[200:203], v[20:23]
	v_mfma_f32_16x16x32_bf16 v[76:79], v[120:123], v[208:211], v[76:79]
	v_mfma_f32_16x16x32_bf16 v[12:15], v[132:135], v[208:211], v[12:15]
	v_mfma_f32_16x16x32_bf16 v[68:71], v[120:123], v[216:219], v[68:71]
	v_mfma_f32_16x16x32_bf16 v[4:7], v[132:135], v[216:219], v[4:7]
	v_mfma_f32_16x16x32_bf16 v[88:91], v[144:147], v[188:191], v[88:91]
	v_mfma_f32_16x16x32_bf16 v[24:27], v[170:173], v[188:191], v[24:27]
	v_mfma_f32_16x16x32_bf16 v[80:83], v[144:147], v[196:199], v[80:83]
	v_mfma_f32_16x16x32_bf16 v[16:19], v[170:173], v[196:199], v[16:19]
	v_mfma_f32_16x16x32_bf16 v[72:75], v[144:147], v[204:207], v[72:75]
	v_mfma_f32_16x16x32_bf16 v[8:11], v[170:173], v[204:207], v[8:11]
	v_mfma_f32_16x16x32_bf16 v[60:63], v[144:147], v[212:215], v[60:63]
	v_mfma_f32_16x16x32_bf16 v[0:3], v[170:173], v[212:215], v[0:3]
	v_mfma_f32_16x16x32_bf16 v[88:91], v[148:151], v[192:195], v[88:91]
	v_mfma_f32_16x16x32_bf16 v[24:27], v[174:177], v[192:195], v[24:27]
	v_mfma_f32_16x16x32_bf16 v[80:83], v[148:151], v[200:203], v[80:83]
	v_mfma_f32_16x16x32_bf16 v[16:19], v[174:177], v[200:203], v[16:19]
	v_mfma_f32_16x16x32_bf16 v[72:75], v[148:151], v[208:211], v[72:75]
	v_mfma_f32_16x16x32_bf16 v[8:11], v[174:177], v[208:211], v[8:11]
	v_mfma_f32_16x16x32_bf16 v[60:63], v[148:151], v[216:219], v[60:63]
	v_mfma_f32_16x16x32_bf16 v[0:3], v[174:177], v[216:219], v[0:3]
	s_setprio 0
	s_barrier
	s_add_i32 s36, 0, 0x18000
	s_add_i32 s37, 0, 0x1c000
	v_add_u32_e32 v132, s36, v182
	v_add_u32_e32 v174, s37, v182
	ds_read_b128 v[116:119], v132
	ds_read_b128 v[120:123], v132 offset:1024
	ds_read_b128 v[128:131], v132 offset:2048
	ds_read_b128 v[132:135], v132 offset:3072
	ds_read_b128 v[144:147], v174
	ds_read_b128 v[148:151], v174 offset:1024
	ds_read_b128 v[170:173], v174 offset:2048
	ds_read_b128 v[174:177], v174 offset:3072
	s_add_u32 s28, s28, 0x40000
	s_addc_u32 s29, s29, 0
	s_mov_b32 m0, s44
	v_lshl_add_u64 v[226:227], s[28:29], 0, v[154:155]
	ds_read_b128 v[188:191], v186 offset:32768
	ds_read_b128 v[192:195], v186 offset:33792
	ds_read_b128 v[196:199], v186 offset:34816
	ds_read_b128 v[200:203], v186 offset:35840
	ds_read_b128 v[204:207], v186 offset:36864
	ds_read_b128 v[208:211], v186 offset:37888
	ds_read_b128 v[212:215], v186 offset:38912
	ds_read_b128 v[216:219], v186 offset:39936
	global_load_lds_dwordx4 v[226:227], off
	v_lshl_add_u64 v[226:227], s[28:29], 0, v[158:159]
	s_mov_b32 m0, s45
	s_nop 0
	global_load_lds_dwordx4 v[226:227], off
	s_waitcnt vmcnt(8)
	s_waitcnt lgkmcnt(0)
	s_barrier
	s_setprio 1
	s_waitcnt lgkmcnt(0)
	v_mfma_f32_16x16x32_bf16 v[140:143], v[116:119], v[188:191], v[140:143]
	v_mfma_f32_16x16x32_bf16 v[64:67], v[128:131], v[188:191], v[64:67]
	v_mfma_f32_16x16x32_bf16 v[124:127], v[116:119], v[196:199], v[124:127]
	v_mfma_f32_16x16x32_bf16 v[52:55], v[128:131], v[196:199], v[52:55]
	v_mfma_f32_16x16x32_bf16 v[108:111], v[116:119], v[204:207], v[108:111]
	v_mfma_f32_16x16x32_bf16 v[44:47], v[128:131], v[204:207], v[44:47]
	v_mfma_f32_16x16x32_bf16 v[100:103], v[116:119], v[212:215], v[100:103]
	v_mfma_f32_16x16x32_bf16 v[36:39], v[128:131], v[212:215], v[36:39]
	v_mfma_f32_16x16x32_bf16 v[140:143], v[120:123], v[192:195], v[140:143]
	v_mfma_f32_16x16x32_bf16 v[64:67], v[132:135], v[192:195], v[64:67]
	v_mfma_f32_16x16x32_bf16 v[124:127], v[120:123], v[200:203], v[124:127]
	v_mfma_f32_16x16x32_bf16 v[52:55], v[132:135], v[200:203], v[52:55]
	v_mfma_f32_16x16x32_bf16 v[108:111], v[120:123], v[208:211], v[108:111]
	v_mfma_f32_16x16x32_bf16 v[44:47], v[132:135], v[208:211], v[44:47]
	v_mfma_f32_16x16x32_bf16 v[100:103], v[120:123], v[216:219], v[100:103]
	v_mfma_f32_16x16x32_bf16 v[36:39], v[132:135], v[216:219], v[36:39]
	v_mfma_f32_16x16x32_bf16 v[136:139], v[144:147], v[188:191], v[136:139]
	v_mfma_f32_16x16x32_bf16 v[56:59], v[170:173], v[188:191], v[56:59]
	v_mfma_f32_16x16x32_bf16 v[112:115], v[144:147], v[196:199], v[112:115]
	v_mfma_f32_16x16x32_bf16 v[48:51], v[170:173], v[196:199], v[48:51]
	v_mfma_f32_16x16x32_bf16 v[104:107], v[144:147], v[204:207], v[104:107]
	v_mfma_f32_16x16x32_bf16 v[40:43], v[170:173], v[204:207], v[40:43]
	v_mfma_f32_16x16x32_bf16 v[96:99], v[144:147], v[212:215], v[96:99]
	v_mfma_f32_16x16x32_bf16 v[32:35], v[170:173], v[212:215], v[32:35]
	v_mfma_f32_16x16x32_bf16 v[136:139], v[148:151], v[192:195], v[136:139]
	v_mfma_f32_16x16x32_bf16 v[56:59], v[174:177], v[192:195], v[56:59]
	v_mfma_f32_16x16x32_bf16 v[112:115], v[148:151], v[200:203], v[112:115]
	v_mfma_f32_16x16x32_bf16 v[48:51], v[174:177], v[200:203], v[48:51]
	v_mfma_f32_16x16x32_bf16 v[104:107], v[148:151], v[208:211], v[104:107]
	v_mfma_f32_16x16x32_bf16 v[40:43], v[174:177], v[208:211], v[40:43]
	v_mfma_f32_16x16x32_bf16 v[96:99], v[148:151], v[216:219], v[96:99]
	v_mfma_f32_16x16x32_bf16 v[32:35], v[174:177], v[216:219], v[32:35]
	s_setprio 0
	s_barrier
; #define PG8_STAGE(bufoff, gbase, voff) do { _Pragma("unroll") for (int _i = 0; _i < 2; ++_i) \
;         __builtin_amdgcn_global_load_lds((const unsigned*)((const char*)(gbase) + (voff)[_i]), (LAS unsigned*)(lds + (bufoff) + ldsw + _i * 8192), 16, 0, 0); } while (0)
; #define PG8_LDA(dst, b, h) do { _Pragma("unroll") for (int m = 0; m < 4; ++m) _Pragma("unroll") for (int k = 0; k < 2; ++k) dst[m][k] = *(const LAS bf16x8*)(lds + PG8_SA(b, h) + aoff + m * 2048 + k * 1024); } while (0)
; #define PG8_MMA(ai, bj, At, Bt) do { __builtin_amdgcn_s_setprio(1); _Pragma("unroll") for (int m = 0; m < 4; ++m) _Pragma("unroll") for (int n = 0; n < 2; ++n) _Pragma("unroll") for (int k = 0; k < 2; ++k) \
;         acc[ai][bj][m][n] = __builtin_amdgcn_mfma_f32_16x16x32_bf16(Bt[n][k], At[m][k], acc[ai][bj][m][n], 0, 0, 0); __builtin_amdgcn_s_setprio(0); } while (0)
; #define PG8_WAIT_V(n) asm volatile("s_waitcnt vmcnt(" #n ")" ::: "memory")
; #define PG8_WAIT_L(n) asm volatile("s_waitcnt lgkmcnt(" #n ")" ::: "memory")
; #define PG8_BAR __builtin_amdgcn_s_barrier()
; #define PG8_SCHED __builtin_amdgcn_sched_barrier(0)
; template <class Epi, class Sched, bool ALIGN_EPI = true>
; __device__ __forceinline__ void gemm_phase(LAS unsigned char* lds, const Gemm g, const Sched& S, const Epi& E) {
;     ...
;             PG8_LDA(At, 1, 1); PG8_STAGE(PG8_SB(1, 0), b3, voffB); PG8_STAGE(PG8_SB(1, 1), b3 + hsB, voffB); PG8_STAGE(PG8_SA(1, 0), a3, voffA);
;             PG8_WAIT_V(8); PG8_WAIT_L(0); PG8_BAR; PG8_MMA(1, 0, At, B0); PG8_MMA(1, 1, At, B1); PG8_BAR; PG8_SCHED;
;         }
	s_add_i32 s28, s36, s33
	v_lshl_add_u64 v[178:179], v[178:179], 0, s[94:95]
	s_mov_b32 m0, s28
	ds_read_b128 v[188:191], v186 offset:49152
	ds_read_b128 v[192:195], v186 offset:50176
	ds_read_b128 v[196:199], v186 offset:51200
	ds_read_b128 v[200:203], v186 offset:52224
	ds_read_b128 v[204:207], v186 offset:53248
	ds_read_b128 v[208:211], v186 offset:54272
	ds_read_b128 v[212:215], v186 offset:55296
	ds_read_b128 v[216:219], v186 offset:56320
	global_load_lds_dwordx4 v[178:179], off
	s_add_i32 m0, s28, 0x2000
	s_add_u32 s26, s26, 0x40080
	v_lshl_add_u64 v[178:179], v[220:221], 0, s[94:95]
	s_addc_u32 s27, s27, 0
	s_add_i32 s28, s37, s33
	global_load_lds_dwordx4 v[178:179], off
	v_lshl_add_u64 v[178:179], s[26:27], 0, v[156:157]
	s_mov_b32 m0, s28
	s_nop 0
	global_load_lds_dwordx4 v[178:179], off
	v_lshl_add_u64 v[178:179], s[26:27], 0, v[160:161]
	s_add_i32 m0, s28, 0x2000
	s_nop 0
	global_load_lds_dwordx4 v[178:179], off
	v_lshl_add_u64 v[178:179], v[222:223], 0, s[94:95]
	s_mov_b32 m0, s48
	s_nop 0
	global_load_lds_dwordx4 v[178:179], off
	v_lshl_add_u64 v[178:179], v[224:225], 0, s[94:95]
	s_mov_b32 m0, s49
	s_nop 0
	global_load_lds_dwordx4 v[178:179], off
	s_waitcnt vmcnt(8)
	s_waitcnt lgkmcnt(0)
	s_barrier
	s_setprio 1
	s_waitcnt lgkmcnt(0)
	v_mfma_f32_16x16x32_bf16 v[92:95], v[116:119], v[188:191], v[92:95]
	v_mfma_f32_16x16x32_bf16 v[28:31], v[128:131], v[188:191], v[28:31]
	v_mfma_f32_16x16x32_bf16 v[84:87], v[116:119], v[196:199], v[84:87]
	v_mfma_f32_16x16x32_bf16 v[20:23], v[128:131], v[196:199], v[20:23]
	v_mfma_f32_16x16x32_bf16 v[76:79], v[116:119], v[204:207], v[76:79]
	v_mfma_f32_16x16x32_bf16 v[12:15], v[128:131], v[204:207], v[12:15]
	v_mfma_f32_16x16x32_bf16 v[68:71], v[116:119], v[212:215], v[68:71]
	v_mfma_f32_16x16x32_bf16 v[4:7], v[128:131], v[212:215], v[4:7]
	v_mfma_f32_16x16x32_bf16 v[92:95], v[120:123], v[192:195], v[92:95]
	v_mfma_f32_16x16x32_bf16 v[28:31], v[132:135], v[192:195], v[28:31]
	v_mfma_f32_16x16x32_bf16 v[84:87], v[120:123], v[200:203], v[84:87]
	v_mfma_f32_16x16x32_bf16 v[20:23], v[132:135], v[200:203], v[20:23]
	v_mfma_f32_16x16x32_bf16 v[76:79], v[120:123], v[208:211], v[76:79]
	v_mfma_f32_16x16x32_bf16 v[12:15], v[132:135], v[208:211], v[12:15]
	v_mfma_f32_16x16x32_bf16 v[68:71], v[120:123], v[216:219], v[68:71]
	v_mfma_f32_16x16x32_bf16 v[4:7], v[132:135], v[216:219], v[4:7]
	v_mfma_f32_16x16x32_bf16 v[88:91], v[144:147], v[188:191], v[88:91]
	v_mfma_f32_16x16x32_bf16 v[24:27], v[170:173], v[188:191], v[24:27]
	v_mfma_f32_16x16x32_bf16 v[80:83], v[144:147], v[196:199], v[80:83]
	v_mfma_f32_16x16x32_bf16 v[16:19], v[170:173], v[196:199], v[16:19]
	v_mfma_f32_16x16x32_bf16 v[72:75], v[144:147], v[204:207], v[72:75]
	v_mfma_f32_16x16x32_bf16 v[8:11], v[170:173], v[204:207], v[8:11]
	v_mfma_f32_16x16x32_bf16 v[60:63], v[144:147], v[212:215], v[60:63]
	v_mfma_f32_16x16x32_bf16 v[0:3], v[170:173], v[212:215], v[0:3]
	v_mfma_f32_16x16x32_bf16 v[88:91], v[148:151], v[192:195], v[88:91]
	v_mfma_f32_16x16x32_bf16 v[24:27], v[174:177], v[192:195], v[24:27]
	v_mfma_f32_16x16x32_bf16 v[80:83], v[148:151], v[200:203], v[80:83]
	v_mfma_f32_16x16x32_bf16 v[16:19], v[174:177], v[200:203], v[16:19]
	v_mfma_f32_16x16x32_bf16 v[72:75], v[148:151], v[208:211], v[72:75]
	v_mfma_f32_16x16x32_bf16 v[8:11], v[174:177], v[208:211], v[8:11]
	v_mfma_f32_16x16x32_bf16 v[60:63], v[148:151], v[216:219], v[60:63]
	v_mfma_f32_16x16x32_bf16 v[0:3], v[174:177], v[216:219], v[0:3]
	s_setprio 0
	s_barrier
	s_add_i32 s35, s35, 2
	s_add_u32 s6, s6, 0x100
	s_addc_u32 s7, s7, 0
	s_add_u32 s31, s31, 0x100
	s_addc_u32 s34, s34, 0
	s_cmp_gt_u32 s35, 13
	s_cbranch_scc0 .LBB0_881
	s_and_b64 vcc, exec, s[96:97]
	s_cbranch_vccz .LBB0_884
	s_barrier

; __device__ __forceinline__ unsigned xb_add(unsigned* p, unsigned v) { return __hip_atomic_fetch_add(p, v, __ATOMIC_RELAXED, __HIP_MEMORY_SCOPE_AGENT); }
; __device__ __forceinline__ void xcd_barrier(const XcdBarrier& b) {
;     ...
;             __builtin_amdgcn_fence(__ATOMIC_ACQUIRE, "agent");
;             xb_add(&bar[XB_XGEN(b.x)], 1u);
;             asm volatile("s_waitcnt vmcnt(0)" ::: "memory");
.LBB0_973:
	s_or_b64 exec, exec, s[6:7]
	s_mov_b64 s[6:7], exec
	v_mbcnt_lo_u32_b32 v0, s6, 0
	v_mbcnt_hi_u32_b32 v0, s7, v0
	v_cmp_eq_u32_e32 vcc, 0, v0
	s_waitcnt vmcnt(0)
	buffer_inv sc1
	s_and_saveexec_b64 s[8:9], vcc
	s_cbranch_execz .LBB0_975
	s_bcnt1_i32_b64 s6, s[6:7]
.LBB0_975:
	s_or_b64 exec, exec, s[8:9]
	s_waitcnt vmcnt(0)

; #define PG8_STAGE(bufoff, gbase, voff) do { _Pragma("unroll") for (int _i = 0; _i < 2; ++_i) \
;         __builtin_amdgcn_global_load_lds((const unsigned*)((const char*)(gbase) + (voff)[_i]), (LAS unsigned*)(lds + (bufoff) + ldsw + _i * 8192), 16, 0, 0); } while (0)
; #define PG8_LDA(dst, b, h) do { _Pragma("unroll") for (int m = 0; m < 4; ++m) _Pragma("unroll") for (int k = 0; k < 2; ++k) dst[m][k] = *(const LAS bf16x8*)(lds + PG8_SA(b, h) + aoff + m * 2048 + k * 1024); } while (0)
; #define PG8_LDB(dst, b, h) do { _Pragma("unroll") for (int n = 0; n < 2; ++n) _Pragma("unroll") for (int k = 0; k < 2; ++k) dst[n][k] = *(const LAS bf16x8*)(lds + PG8_SB(b, h) + boff + n * 2048 + k * 1024); } while (0)
; #define PG8_MMA(ai, bj, At, Bt) do { __builtin_amdgcn_s_setprio(1); _Pragma("unroll") for (int m = 0; m < 4; ++m) _Pragma("unroll") for (int n = 0; n < 2; ++n) _Pragma("unroll") for (int k = 0; k < 2; ++k) \
;         acc[ai][bj][m][n] = __builtin_amdgcn_mfma_f32_16x16x32_bf16(Bt[n][k], At[m][k], acc[ai][bj][m][n], 0, 0, 0); __builtin_amdgcn_s_setprio(0); } while (0)
; #define PG8_WAIT_V(n) asm volatile("s_waitcnt vmcnt(" #n ")" ::: "memory")
; #define PG8_WAIT_L(n) asm volatile("s_waitcnt lgkmcnt(" #n ")" ::: "memory")
; #define PG8_BAR __builtin_amdgcn_s_barrier()
; #define PG8_SCHED __builtin_amdgcn_sched_barrier(0)
; template <class Epi, class Sched, bool ALIGN_EPI = true>
; __device__ __forceinline__ void gemm_phase(LAS unsigned char* lds, const Gemm g, const Sched& S, const Epi& E) {
;     ...
;             const bool last = (t == nt - 2);
;             const char* a1 = cA + (size_t)(t + 1) * kstep;
;             const char* a2 = last ? nA : cA + (size_t)(t + 2) * kstep; const char* b2 = last ? nB : cB + (size_t)(t + 2) * kstep;
;             const char* a3 = a2 + kstep; const char* b3 = b2 + kstep;
;             PG8_LDB(B0, 0, 0); PG8_LDB(B1, 0, 1); PG8_SCHED; PG8_LDA(At, 0, 0); PG8_STAGE(PG8_SA(1, 1), a1 + hsA, voffA);
;             PG8_WAIT_V(8); PG8_WAIT_L(0); PG8_BAR; PG8_MMA(0, 0, At, B0); PG8_MMA(0, 1, At, B1); PG8_BAR; PG8_SCHED;
;             PG8_LDA(At, 0, 1); PG8_STAGE(PG8_SB(0, 0), b2, voffB); PG8_STAGE(PG8_SB(0, 1), b2 + hsB, voffB); PG8_STAGE(PG8_SA(0, 0), a2, voffA);
;             PG8_WAIT_V(8); PG8_WAIT_L(0); PG8_BAR; PG8_MMA(1, 0, At, B0); PG8_MMA(1, 1, At, B1); PG8_BAR; PG8_SCHED;
.LBB0_999:
	ds_read_b128 v[144:147], v156
	ds_read_b128 v[148:151], v156 offset:1024
	ds_read_b128 v[160:163], v156 offset:2048
	ds_read_b128 v[164:167], v156 offset:3072
	ds_read_b128 v[168:171], v157
	ds_read_b128 v[172:175], v157 offset:1024
	ds_read_b128 v[176:179], v157 offset:2048
	ds_read_b128 v[182:185], v157 offset:3072
	s_add_u32 s4, s26, 0x100
	s_addc_u32 s5, s27, 0
	s_cmp_eq_u32 s53, 40
	s_cselect_b32 s31, s23, s5
	s_cselect_b32 s30, s22, s4
	s_cselect_b32 s29, s25, s52
	s_cselect_b32 s28, s24, s51
	v_lshl_add_u64 v[218:219], s[26:27], 0, v[136:137]
	s_add_i32 m0, s34, 0xc000
	ds_read_b128 v[186:189], v158
	ds_read_b128 v[190:193], v158 offset:1024
	ds_read_b128 v[194:197], v158 offset:2048
	ds_read_b128 v[198:201], v158 offset:3072
	ds_read_b128 v[202:205], v158 offset:4096
	ds_read_b128 v[206:209], v158 offset:5120
	ds_read_b128 v[210:213], v158 offset:6144
	ds_read_b128 v[214:217], v158 offset:7168
	global_load_lds_dwordx4 v[218:219], off
	v_lshl_add_u64 v[218:219], s[26:27], 0, v[138:139]
	s_add_i32 m0, s34, 0xe000
	s_nop 0
	global_load_lds_dwordx4 v[218:219], off
	s_waitcnt vmcnt(8)
	s_waitcnt lgkmcnt(0)
	s_barrier
	s_setprio 1
	s_waitcnt lgkmcnt(0)
	v_mfma_f32_16x16x32_bf16 v[124:127], v[144:147], v[186:189], v[124:127]
	v_mfma_f32_16x16x32_bf16 v[120:123], v[160:163], v[186:189], v[120:123]
	v_mfma_f32_16x16x32_bf16 v[112:115], v[144:147], v[194:197], v[112:115]
	v_mfma_f32_16x16x32_bf16 v[104:107], v[160:163], v[194:197], v[104:107]
	v_mfma_f32_16x16x32_bf16 v[96:99], v[144:147], v[202:205], v[96:99]
	v_mfma_f32_16x16x32_bf16 v[88:91], v[160:163], v[202:205], v[88:91]
	v_mfma_f32_16x16x32_bf16 v[80:83], v[144:147], v[210:213], v[80:83]
	v_mfma_f32_16x16x32_bf16 v[72:75], v[160:163], v[210:213], v[72:75]
	v_mfma_f32_16x16x32_bf16 v[124:127], v[148:151], v[190:193], v[124:127]
	v_mfma_f32_16x16x32_bf16 v[120:123], v[164:167], v[190:193], v[120:123]
	v_mfma_f32_16x16x32_bf16 v[112:115], v[148:151], v[198:201], v[112:115]
	v_mfma_f32_16x16x32_bf16 v[104:107], v[164:167], v[198:201], v[104:107]
	v_mfma_f32_16x16x32_bf16 v[96:99], v[148:151], v[206:209], v[96:99]
	v_mfma_f32_16x16x32_bf16 v[88:91], v[164:167], v[206:209], v[88:91]
	v_mfma_f32_16x16x32_bf16 v[80:83], v[148:151], v[214:217], v[80:83]
	v_mfma_f32_16x16x32_bf16 v[72:75], v[164:167], v[214:217], v[72:75]
	v_mfma_f32_16x16x32_bf16 v[116:119], v[168:171], v[186:189], v[116:119]
	v_mfma_f32_16x16x32_bf16 v[108:111], v[176:179], v[186:189], v[108:111]
	v_mfma_f32_16x16x32_bf16 v[100:103], v[168:171], v[194:197], v[100:103]
	v_mfma_f32_16x16x32_bf16 v[92:95], v[176:179], v[194:197], v[92:95]
	v_mfma_f32_16x16x32_bf16 v[84:87], v[168:171], v[202:205], v[84:87]
	v_mfma_f32_16x16x32_bf16 v[76:79], v[176:179], v[202:205], v[76:79]
	v_mfma_f32_16x16x32_bf16 v[68:71], v[168:171], v[210:213], v[68:71]
	v_mfma_f32_16x16x32_bf16 v[64:67], v[176:179], v[210:213], v[64:67]
	v_mfma_f32_16x16x32_bf16 v[116:119], v[172:175], v[190:193], v[116:119]
	v_mfma_f32_16x16x32_bf16 v[108:111], v[182:185], v[190:193], v[108:111]
	v_mfma_f32_16x16x32_bf16 v[100:103], v[172:175], v[198:201], v[100:103]
	v_mfma_f32_16x16x32_bf16 v[92:95], v[182:185], v[198:201], v[92:95]
	v_mfma_f32_16x16x32_bf16 v[84:87], v[172:175], v[206:209], v[84:87]
	v_mfma_f32_16x16x32_bf16 v[76:79], v[182:185], v[206:209], v[76:79]
	v_mfma_f32_16x16x32_bf16 v[68:71], v[172:175], v[214:217], v[68:71]
	v_mfma_f32_16x16x32_bf16 v[64:67], v[182:185], v[214:217], v[64:67]
	s_setprio 0
	s_barrier
	s_add_i32 s26, s45, s33
	v_lshl_add_u64 v[218:219], s[28:29], 0, v[130:131]
	s_mov_b32 m0, s26
	ds_read_b128 v[186:189], v158 offset:16384
	ds_read_b128 v[190:193], v158 offset:17408
	ds_read_b128 v[194:197], v158 offset:18432
	ds_read_b128 v[198:201], v158 offset:19456
	ds_read_b128 v[202:205], v158 offset:20480
	ds_read_b128 v[206:209], v158 offset:21504
	ds_read_b128 v[210:213], v158 offset:22528
	ds_read_b128 v[214:217], v158 offset:23552
	global_load_lds_dwordx4 v[218:219], off
	s_add_i32 m0, s26, 0x2000
	s_add_u32 s26, s28, 0xb0000
	v_lshl_add_u64 v[220:221], s[28:29], 0, v[134:135]
	s_addc_u32 s27, s29, 0
	s_add_i32 s54, s46, s33
	global_load_lds_dwordx4 v[220:221], off
	v_lshl_add_u64 v[222:223], s[26:27], 0, v[130:131]
	s_mov_b32 m0, s54
	v_lshl_add_u64 v[224:225], s[30:31], 0, v[132:133]
	global_load_lds_dwordx4 v[222:223], off
	v_lshl_add_u64 v[222:223], s[26:27], 0, v[134:135]
	s_add_i32 m0, s54, 0x2000
	s_nop 0
	global_load_lds_dwordx4 v[222:223], off
	v_lshl_add_u64 v[222:223], s[30:31], 0, v[128:129]
	s_mov_b32 m0, s34
	s_nop 0
	global_load_lds_dwordx4 v[222:223], off
	s_mov_b32 m0, s35
	s_nop 0
	global_load_lds_dwordx4 v[224:225], off
	s_waitcnt vmcnt(8)
	s_waitcnt lgkmcnt(0)
	s_barrier
; #define PG8_STAGE(bufoff, gbase, voff) do { _Pragma("unroll") for (int _i = 0; _i < 2; ++_i) \
;         __builtin_amdgcn_global_load_lds((const unsigned*)((const char*)(gbase) + (voff)[_i]), (LAS unsigned*)(lds + (bufoff) + ldsw + _i * 8192), 16, 0, 0); } while (0)
; #define PG8_LDA(dst, b, h) do { _Pragma("unroll") for (int m = 0; m < 4; ++m) _Pragma("unroll") for (int k = 0; k < 2; ++k) dst[m][k] = *(const LAS bf16x8*)(lds + PG8_SA(b, h) + aoff + m * 2048 + k * 1024); } while (0)
; #define PG8_LDB(dst, b, h) do { _Pragma("unroll") for (int n = 0; n < 2; ++n) _Pragma("unroll") for (int k = 0; k < 2; ++k) dst[n][k] = *(const LAS bf16x8*)(lds + PG8_SB(b, h) + boff + n * 2048 + k * 1024); } while (0)
; #define PG8_MMA(ai, bj, At, Bt) do { __builtin_amdgcn_s_setprio(1); _Pragma("unroll") for (int m = 0; m < 4; ++m) _Pragma("unroll") for (int n = 0; n < 2; ++n) _Pragma("unroll") for (int k = 0; k < 2; ++k) \
;         acc[ai][bj][m][n] = __builtin_amdgcn_mfma_f32_16x16x32_bf16(Bt[n][k], At[m][k], acc[ai][bj][m][n], 0, 0, 0); __builtin_amdgcn_s_setprio(0); } while (0)
; #define PG8_WAIT_V(n) asm volatile("s_waitcnt vmcnt(" #n ")" ::: "memory")
; #define PG8_WAIT_L(n) asm volatile("s_waitcnt lgkmcnt(" #n ")" ::: "memory")
; #define PG8_BAR __builtin_amdgcn_s_barrier()
; #define PG8_SCHED __builtin_amdgcn_sched_barrier(0)
; template <class Epi, class Sched, bool ALIGN_EPI = true>
; __device__ __forceinline__ void gemm_phase(LAS unsigned char* lds, const Gemm g, const Sched& S, const Epi& E) {
;     ...
;             PG8_WAIT_V(8); PG8_WAIT_L(0); PG8_BAR; PG8_MMA(1, 0, At, B0); PG8_MMA(1, 1, At, B1); PG8_BAR; PG8_SCHED;
;             PG8_LDB(B0, 1, 0); PG8_LDB(B1, 1, 1); PG8_SCHED; PG8_LDA(At, 1, 0); PG8_STAGE(PG8_SA(0, 1), a2 + hsA, voffA);
;             PG8_WAIT_V(8); PG8_WAIT_L(0); PG8_BAR; PG8_MMA(0, 0, At, B0); PG8_MMA(0, 1, At, B1); PG8_BAR; PG8_SCHED;
	s_setprio 1
	s_waitcnt lgkmcnt(0)
	v_mfma_f32_16x16x32_bf16 v[60:63], v[144:147], v[186:189], v[60:63]
	v_mfma_f32_16x16x32_bf16 v[56:59], v[160:163], v[186:189], v[56:59]
	v_mfma_f32_16x16x32_bf16 v[48:51], v[144:147], v[194:197], v[48:51]
	v_mfma_f32_16x16x32_bf16 v[40:43], v[160:163], v[194:197], v[40:43]
	v_mfma_f32_16x16x32_bf16 v[32:35], v[144:147], v[202:205], v[32:35]
	v_mfma_f32_16x16x32_bf16 v[24:27], v[160:163], v[202:205], v[24:27]
	v_mfma_f32_16x16x32_bf16 v[16:19], v[144:147], v[210:213], v[16:19]
	v_mfma_f32_16x16x32_bf16 v[8:11], v[160:163], v[210:213], v[8:11]
	v_mfma_f32_16x16x32_bf16 v[60:63], v[148:151], v[190:193], v[60:63]
	v_mfma_f32_16x16x32_bf16 v[56:59], v[164:167], v[190:193], v[56:59]
	v_mfma_f32_16x16x32_bf16 v[48:51], v[148:151], v[198:201], v[48:51]
	v_mfma_f32_16x16x32_bf16 v[40:43], v[164:167], v[198:201], v[40:43]
	v_mfma_f32_16x16x32_bf16 v[32:35], v[148:151], v[206:209], v[32:35]
	v_mfma_f32_16x16x32_bf16 v[24:27], v[164:167], v[206:209], v[24:27]
	v_mfma_f32_16x16x32_bf16 v[16:19], v[148:151], v[214:217], v[16:19]
	v_mfma_f32_16x16x32_bf16 v[8:11], v[164:167], v[214:217], v[8:11]
	v_mfma_f32_16x16x32_bf16 v[52:55], v[168:171], v[186:189], v[52:55]
	v_mfma_f32_16x16x32_bf16 v[44:47], v[176:179], v[186:189], v[44:47]
	v_mfma_f32_16x16x32_bf16 v[36:39], v[168:171], v[194:197], v[36:39]
	v_mfma_f32_16x16x32_bf16 v[28:31], v[176:179], v[194:197], v[28:31]
	v_mfma_f32_16x16x32_bf16 v[20:23], v[168:171], v[202:205], v[20:23]
	v_mfma_f32_16x16x32_bf16 v[12:15], v[176:179], v[202:205], v[12:15]
	v_mfma_f32_16x16x32_bf16 v[4:7], v[168:171], v[210:213], v[4:7]
	v_mfma_f32_16x16x32_bf16 v[0:3], v[176:179], v[210:213], v[0:3]
	v_mfma_f32_16x16x32_bf16 v[52:55], v[172:175], v[190:193], v[52:55]
	v_mfma_f32_16x16x32_bf16 v[44:47], v[182:185], v[190:193], v[44:47]
	v_mfma_f32_16x16x32_bf16 v[36:39], v[172:175], v[198:201], v[36:39]
	v_mfma_f32_16x16x32_bf16 v[28:31], v[182:185], v[198:201], v[28:31]
	v_mfma_f32_16x16x32_bf16 v[20:23], v[172:175], v[206:209], v[20:23]
	v_mfma_f32_16x16x32_bf16 v[12:15], v[182:185], v[206:209], v[12:15]
	v_mfma_f32_16x16x32_bf16 v[4:7], v[172:175], v[214:217], v[4:7]
	v_mfma_f32_16x16x32_bf16 v[0:3], v[182:185], v[214:217], v[0:3]
	s_setprio 0
	s_barrier
	s_add_i32 s54, 0, 0x18000
	v_add_u32_e32 v159, s54, v154
	s_add_i32 s55, 0, 0x1c000
	ds_read_b128 v[144:147], v159
	ds_read_b128 v[148:151], v159 offset:1024
	ds_read_b128 v[160:163], v159 offset:2048
	ds_read_b128 v[164:167], v159 offset:3072
	v_add_u32_e32 v159, s55, v154
	ds_read_b128 v[168:171], v159
	ds_read_b128 v[172:175], v159 offset:1024
	ds_read_b128 v[176:179], v159 offset:2048
	ds_read_b128 v[182:185], v159 offset:3072
	s_add_u32 s26, s30, 0xb0000
	s_addc_u32 s27, s31, 0
	s_mov_b32 m0, s36
	v_lshl_add_u64 v[226:227], s[26:27], 0, v[128:129]
	ds_read_b128 v[186:189], v158 offset:32768
	ds_read_b128 v[190:193], v158 offset:33792
	ds_read_b128 v[194:197], v158 offset:34816
	ds_read_b128 v[198:201], v158 offset:35840
	ds_read_b128 v[202:205], v158 offset:36864
	ds_read_b128 v[206:209], v158 offset:37888
	ds_read_b128 v[210:213], v158 offset:38912
	ds_read_b128 v[214:217], v158 offset:39936
	global_load_lds_dwordx4 v[226:227], off
	v_lshl_add_u64 v[226:227], s[26:27], 0, v[132:133]
	s_mov_b32 m0, s37
	s_nop 0
	global_load_lds_dwordx4 v[226:227], off
	s_waitcnt vmcnt(8)
	s_waitcnt lgkmcnt(0)
	s_barrier
	s_setprio 1
	s_waitcnt lgkmcnt(0)
	v_mfma_f32_16x16x32_bf16 v[124:127], v[144:147], v[186:189], v[124:127]
	v_mfma_f32_16x16x32_bf16 v[120:123], v[160:163], v[186:189], v[120:123]
	v_mfma_f32_16x16x32_bf16 v[112:115], v[144:147], v[194:197], v[112:115]
	v_mfma_f32_16x16x32_bf16 v[104:107], v[160:163], v[194:197], v[104:107]
	v_mfma_f32_16x16x32_bf16 v[96:99], v[144:147], v[202:205], v[96:99]
	v_mfma_f32_16x16x32_bf16 v[88:91], v[160:163], v[202:205], v[88:91]
	v_mfma_f32_16x16x32_bf16 v[80:83], v[144:147], v[210:213], v[80:83]
	v_mfma_f32_16x16x32_bf16 v[72:75], v[160:163], v[210:213], v[72:75]
	v_mfma_f32_16x16x32_bf16 v[124:127], v[148:151], v[190:193], v[124:127]
	v_mfma_f32_16x16x32_bf16 v[120:123], v[164:167], v[190:193], v[120:123]
	v_mfma_f32_16x16x32_bf16 v[112:115], v[148:151], v[198:201], v[112:115]
	v_mfma_f32_16x16x32_bf16 v[104:107], v[164:167], v[198:201], v[104:107]
	v_mfma_f32_16x16x32_bf16 v[96:99], v[148:151], v[206:209], v[96:99]
	v_mfma_f32_16x16x32_bf16 v[88:91], v[164:167], v[206:209], v[88:91]
	v_mfma_f32_16x16x32_bf16 v[80:83], v[148:151], v[214:217], v[80:83]
	v_mfma_f32_16x16x32_bf16 v[72:75], v[164:167], v[214:217], v[72:75]
	v_mfma_f32_16x16x32_bf16 v[116:119], v[168:171], v[186:189], v[116:119]
	v_mfma_f32_16x16x32_bf16 v[108:111], v[176:179], v[186:189], v[108:111]
	v_mfma_f32_16x16x32_bf16 v[100:103], v[168:171], v[194:197], v[100:103]
	v_mfma_f32_16x16x32_bf16 v[92:95], v[176:179], v[194:197], v[92:95]
	v_mfma_f32_16x16x32_bf16 v[84:87], v[168:171], v[202:205], v[84:87]
	v_mfma_f32_16x16x32_bf16 v[76:79], v[176:179], v[202:205], v[76:79]
	v_mfma_f32_16x16x32_bf16 v[68:71], v[168:171], v[210:213], v[68:71]
	v_mfma_f32_16x16x32_bf16 v[64:67], v[176:179], v[210:213], v[64:67]
	v_mfma_f32_16x16x32_bf16 v[116:119], v[172:175], v[190:193], v[116:119]
	v_mfma_f32_16x16x32_bf16 v[108:111], v[182:185], v[190:193], v[108:111]
	v_mfma_f32_16x16x32_bf16 v[100:103], v[172:175], v[198:201], v[100:103]
	v_mfma_f32_16x16x32_bf16 v[92:95], v[182:185], v[198:201], v[92:95]
	v_mfma_f32_16x16x32_bf16 v[84:87], v[172:175], v[206:209], v[84:87]
	v_mfma_f32_16x16x32_bf16 v[76:79], v[182:185], v[206:209], v[76:79]
	v_mfma_f32_16x16x32_bf16 v[68:71], v[172:175], v[214:217], v[68:71]
	v_mfma_f32_16x16x32_bf16 v[64:67], v[182:185], v[214:217], v[64:67]
	s_setprio 0
	s_barrier
; #define PG8_STAGE(bufoff, gbase, voff) do { _Pragma("unroll") for (int _i = 0; _i < 2; ++_i) \
;         __builtin_amdgcn_global_load_lds((const unsigned*)((const char*)(gbase) + (voff)[_i]), (LAS unsigned*)(lds + (bufoff) + ldsw + _i * 8192), 16, 0, 0); } while (0)
; #define PG8_LDA(dst, b, h) do { _Pragma("unroll") for (int m = 0; m < 4; ++m) _Pragma("unroll") for (int k = 0; k < 2; ++k) dst[m][k] = *(const LAS bf16x8*)(lds + PG8_SA(b, h) + aoff + m * 2048 + k * 1024); } while (0)
; #define PG8_MMA(ai, bj, At, Bt) do { __builtin_amdgcn_s_setprio(1); _Pragma("unroll") for (int m = 0; m < 4; ++m) _Pragma("unroll") for (int n = 0; n < 2; ++n) _Pragma("unroll") for (int k = 0; k < 2; ++k) \
;         acc[ai][bj][m][n] = __builtin_amdgcn_mfma_f32_16x16x32_bf16(Bt[n][k], At[m][k], acc[ai][bj][m][n], 0, 0, 0); __builtin_amdgcn_s_setprio(0); } while (0)
; #define PG8_WAIT_V(n) asm volatile("s_waitcnt vmcnt(" #n ")" ::: "memory")
; #define PG8_WAIT_L(n) asm volatile("s_waitcnt lgkmcnt(" #n ")" ::: "memory")
; #define PG8_BAR __builtin_amdgcn_s_barrier()
; #define PG8_SCHED __builtin_amdgcn_sched_barrier(0)
; template <class Epi, class Sched, bool ALIGN_EPI = true>
; __device__ __forceinline__ void gemm_phase(LAS unsigned char* lds, const Gemm g, const Sched& S, const Epi& E) {
;     ...
;             PG8_LDA(At, 1, 1); PG8_STAGE(PG8_SB(1, 0), b3, voffB); PG8_STAGE(PG8_SB(1, 1), b3 + hsB, voffB); PG8_STAGE(PG8_SA(1, 0), a3, voffA);
;             PG8_WAIT_V(8); PG8_WAIT_L(0); PG8_BAR; PG8_MMA(1, 0, At, B0); PG8_MMA(1, 1, At, B1); PG8_BAR; PG8_SCHED;
;         }
	s_add_i32 s26, s54, s33
	v_lshl_add_u64 v[218:219], v[218:219], 0, s[8:9]
	s_mov_b32 m0, s26
	ds_read_b128 v[186:189], v158 offset:49152
	ds_read_b128 v[190:193], v158 offset:50176
	ds_read_b128 v[194:197], v158 offset:51200
	ds_read_b128 v[198:201], v158 offset:52224
	ds_read_b128 v[202:205], v158 offset:53248
	ds_read_b128 v[206:209], v158 offset:54272
	ds_read_b128 v[210:213], v158 offset:55296
	ds_read_b128 v[214:217], v158 offset:56320
	global_load_lds_dwordx4 v[218:219], off
	s_add_i32 m0, s26, 0x2000
	s_add_u32 s26, s28, 0xb0080
	v_lshl_add_u64 v[218:219], v[220:221], 0, s[8:9]
	s_addc_u32 s27, s29, 0
	s_add_i32 s28, s55, s33
	global_load_lds_dwordx4 v[218:219], off
	v_lshl_add_u64 v[218:219], s[26:27], 0, v[130:131]
	s_mov_b32 m0, s28
	s_nop 0
	global_load_lds_dwordx4 v[218:219], off
	v_lshl_add_u64 v[218:219], s[26:27], 0, v[134:135]
	s_add_i32 m0, s28, 0x2000
	s_nop 0
	global_load_lds_dwordx4 v[218:219], off
	v_lshl_add_u64 v[218:219], v[222:223], 0, s[8:9]
	s_mov_b32 m0, s40
	s_nop 0
	global_load_lds_dwordx4 v[218:219], off
	v_lshl_add_u64 v[218:219], v[224:225], 0, s[8:9]
	s_mov_b32 m0, s41
	s_nop 0
	global_load_lds_dwordx4 v[218:219], off
	s_waitcnt vmcnt(8)
	s_waitcnt lgkmcnt(0)
	s_barrier
	s_setprio 1
	s_waitcnt lgkmcnt(0)
	v_mfma_f32_16x16x32_bf16 v[60:63], v[144:147], v[186:189], v[60:63]
	v_mfma_f32_16x16x32_bf16 v[56:59], v[160:163], v[186:189], v[56:59]
	v_mfma_f32_16x16x32_bf16 v[48:51], v[144:147], v[194:197], v[48:51]
	v_mfma_f32_16x16x32_bf16 v[40:43], v[160:163], v[194:197], v[40:43]
	v_mfma_f32_16x16x32_bf16 v[32:35], v[144:147], v[202:205], v[32:35]
	v_mfma_f32_16x16x32_bf16 v[24:27], v[160:163], v[202:205], v[24:27]
	v_mfma_f32_16x16x32_bf16 v[16:19], v[144:147], v[210:213], v[16:19]
	v_mfma_f32_16x16x32_bf16 v[8:11], v[160:163], v[210:213], v[8:11]
	v_mfma_f32_16x16x32_bf16 v[60:63], v[148:151], v[190:193], v[60:63]
	v_mfma_f32_16x16x32_bf16 v[56:59], v[164:167], v[190:193], v[56:59]
	v_mfma_f32_16x16x32_bf16 v[48:51], v[148:151], v[198:201], v[48:51]
	v_mfma_f32_16x16x32_bf16 v[40:43], v[164:167], v[198:201], v[40:43]
	v_mfma_f32_16x16x32_bf16 v[32:35], v[148:151], v[206:209], v[32:35]
	v_mfma_f32_16x16x32_bf16 v[24:27], v[164:167], v[206:209], v[24:27]
	v_mfma_f32_16x16x32_bf16 v[16:19], v[148:151], v[214:217], v[16:19]
	v_mfma_f32_16x16x32_bf16 v[8:11], v[164:167], v[214:217], v[8:11]
	v_mfma_f32_16x16x32_bf16 v[52:55], v[168:171], v[186:189], v[52:55]
	v_mfma_f32_16x16x32_bf16 v[44:47], v[176:179], v[186:189], v[44:47]
	v_mfma_f32_16x16x32_bf16 v[36:39], v[168:171], v[194:197], v[36:39]
	v_mfma_f32_16x16x32_bf16 v[28:31], v[176:179], v[194:197], v[28:31]
	v_mfma_f32_16x16x32_bf16 v[20:23], v[168:171], v[202:205], v[20:23]
	v_mfma_f32_16x16x32_bf16 v[12:15], v[176:179], v[202:205], v[12:15]
	v_mfma_f32_16x16x32_bf16 v[4:7], v[168:171], v[210:213], v[4:7]
	v_mfma_f32_16x16x32_bf16 v[0:3], v[176:179], v[210:213], v[0:3]
	v_mfma_f32_16x16x32_bf16 v[52:55], v[172:175], v[190:193], v[52:55]
	v_mfma_f32_16x16x32_bf16 v[44:47], v[182:185], v[190:193], v[44:47]
	v_mfma_f32_16x16x32_bf16 v[36:39], v[172:175], v[198:201], v[36:39]
	v_mfma_f32_16x16x32_bf16 v[28:31], v[182:185], v[198:201], v[28:31]
	v_mfma_f32_16x16x32_bf16 v[20:23], v[172:175], v[206:209], v[20:23]
	v_mfma_f32_16x16x32_bf16 v[12:15], v[182:185], v[206:209], v[12:15]
	v_mfma_f32_16x16x32_bf16 v[4:7], v[172:175], v[214:217], v[4:7]
	v_mfma_f32_16x16x32_bf16 v[0:3], v[182:185], v[214:217], v[0:3]
	s_setprio 0
	s_barrier
	s_add_i32 s53, s53, 2
	s_add_u32 s51, s51, 0x100
	s_addc_u32 s52, s52, 0
	s_cmp_gt_u32 s53, 41
	s_mov_b64 s[26:27], s[4:5]
	s_cbranch_scc0 .LBB0_999
	s_and_b64 vcc, exec, s[12:13]
	s_cbranch_vccz .LBB0_1002
	s_barrier

; __device__ __forceinline__ unsigned xb_add(unsigned* p, unsigned v) { return __hip_atomic_fetch_add(p, v, __ATOMIC_RELAXED, __HIP_MEMORY_SCOPE_AGENT); }
; __device__ __forceinline__ void xcd_barrier(const XcdBarrier& b) {
;     ...
;             __builtin_amdgcn_fence(__ATOMIC_ACQUIRE, "agent");
;             xb_add(&bar[XB_XGEN(b.x)], 1u);
;             asm volatile("s_waitcnt vmcnt(0)" ::: "memory");
.LBB0_1087:
	s_or_b64 exec, exec, s[6:7]
	s_mov_b64 s[6:7], exec
	v_mbcnt_lo_u32_b32 v0, s6, 0
	v_mbcnt_hi_u32_b32 v0, s7, v0
	v_cmp_eq_u32_e32 vcc, 0, v0
	s_waitcnt vmcnt(0)
	buffer_inv sc1
	s_and_saveexec_b64 s[8:9], vcc
	s_cbranch_execz .LBB0_1089
	s_bcnt1_i32_b64 s6, s[6:7]
.LBB0_1089:
	s_or_b64 exec, exec, s[8:9]
	s_waitcnt vmcnt(0)
